# v2 + all six GEMM K-loops issue their LDS-DMA group before the ds_read group in every load segment
# baseline (speedup 1.0000x reference)
.LBB0_160:
	s_add_u32 s16, s14, 0xfff80080
	s_addc_u32 s17, s15, -1
	s_add_i32 s48, 0, 0x10000
	s_cmp_eq_u32 s47, 28
	s_cselect_b32 s19, s5, s17
	s_cselect_b32 s18, s43, s16
	s_cselect_b32 s17, s7, s46
	s_cselect_b32 s16, s44, s45
	s_add_i32 s50, 0, 0x14000
	v_lshl_add_u64 v[204:205], s[14:15], 0, v[150:151]
	s_add_i32 m0, s28, 0xc000
	s_nop 0
	global_load_lds_dwordx4 v[204:205], off
	v_lshl_add_u64 v[204:205], s[14:15], 0, v[152:153]
	s_add_i32 m0, s28, 0xe000
	s_nop 0
	global_load_lds_dwordx4 v[204:205], off
	v_add_u32_e32 v168, s48, v158
	v_add_u32_e32 v184, s50, v158
	ds_read_b128 v[154:157], v168
	ds_read_b128 v[160:163], v168 offset:1024
	ds_read_b128 v[164:167], v168 offset:2048
	ds_read_b128 v[168:171], v168 offset:3072
	ds_read_b128 v[172:175], v184
	ds_read_b128 v[176:179], v184 offset:1024
	ds_read_b128 v[180:183], v184 offset:2048
	ds_read_b128 v[184:187], v184 offset:3072
	ds_read_b128 v[188:191], v159
	ds_read_b128 v[192:195], v159 offset:1024
	ds_read_b128 v[196:199], v159 offset:2048
	ds_read_b128 v[200:203], v159 offset:3072
	ds_read_b128 v[214:217], v159 offset:4096
	ds_read_b128 v[218:221], v159 offset:5120
	ds_read_b128 v[222:225], v159 offset:6144
	ds_read_b128 v[226:229], v159 offset:7168
	s_waitcnt vmcnt(8)
	s_waitcnt lgkmcnt(0)
	s_barrier
	s_setprio 1
	s_waitcnt lgkmcnt(0)
	v_mfma_f32_16x16x32_bf16 v[128:131], v[154:157], v[188:191], v[128:131]
	v_mfma_f32_16x16x32_bf16 v[120:123], v[164:167], v[188:191], v[120:123]
	v_mfma_f32_16x16x32_bf16 v[112:115], v[154:157], v[196:199], v[112:115]
	v_mfma_f32_16x16x32_bf16 v[104:107], v[164:167], v[196:199], v[104:107]
	v_mfma_f32_16x16x32_bf16 v[96:99], v[154:157], v[214:217], v[96:99]
	v_mfma_f32_16x16x32_bf16 v[88:91], v[164:167], v[214:217], v[88:91]
	v_mfma_f32_16x16x32_bf16 v[80:83], v[154:157], v[222:225], v[80:83]
	v_mfma_f32_16x16x32_bf16 v[72:75], v[164:167], v[222:225], v[72:75]
	v_mfma_f32_16x16x32_bf16 v[128:131], v[160:163], v[192:195], v[128:131]
	v_mfma_f32_16x16x32_bf16 v[120:123], v[168:171], v[192:195], v[120:123]
	v_mfma_f32_16x16x32_bf16 v[112:115], v[160:163], v[200:203], v[112:115]
	v_mfma_f32_16x16x32_bf16 v[104:107], v[168:171], v[200:203], v[104:107]
	v_mfma_f32_16x16x32_bf16 v[96:99], v[160:163], v[218:221], v[96:99]
	v_mfma_f32_16x16x32_bf16 v[88:91], v[168:171], v[218:221], v[88:91]
	v_mfma_f32_16x16x32_bf16 v[80:83], v[160:163], v[226:229], v[80:83]
	v_mfma_f32_16x16x32_bf16 v[72:75], v[168:171], v[226:229], v[72:75]
	s_setprio 0
	s_setprio 1
	v_mfma_f32_16x16x32_bf16 v[124:127], v[172:175], v[188:191], v[124:127]
	v_mfma_f32_16x16x32_bf16 v[116:119], v[180:183], v[188:191], v[116:119]
	v_mfma_f32_16x16x32_bf16 v[108:111], v[172:175], v[196:199], v[108:111]
	v_mfma_f32_16x16x32_bf16 v[100:103], v[180:183], v[196:199], v[100:103]
	v_mfma_f32_16x16x32_bf16 v[92:95], v[172:175], v[214:217], v[92:95]
	v_mfma_f32_16x16x32_bf16 v[84:87], v[180:183], v[214:217], v[84:87]
	v_mfma_f32_16x16x32_bf16 v[76:79], v[172:175], v[222:225], v[76:79]
	v_mfma_f32_16x16x32_bf16 v[68:71], v[180:183], v[222:225], v[68:71]
	v_mfma_f32_16x16x32_bf16 v[124:127], v[176:179], v[192:195], v[124:127]
	v_mfma_f32_16x16x32_bf16 v[116:119], v[184:187], v[192:195], v[116:119]
	v_mfma_f32_16x16x32_bf16 v[108:111], v[176:179], v[200:203], v[108:111]
	v_mfma_f32_16x16x32_bf16 v[100:103], v[184:187], v[200:203], v[100:103]
	v_mfma_f32_16x16x32_bf16 v[92:95], v[176:179], v[218:221], v[92:95]
	v_mfma_f32_16x16x32_bf16 v[84:87], v[184:187], v[218:221], v[84:87]
	v_mfma_f32_16x16x32_bf16 v[76:79], v[176:179], v[226:229], v[76:79]
	v_mfma_f32_16x16x32_bf16 v[68:71], v[184:187], v[226:229], v[68:71]
	s_setprio 0
	s_barrier
	s_add_i32 s48, s48, s27
	v_lshl_add_u64 v[204:205], s[16:17], 0, v[136:137]
	s_mov_b32 m0, s48
	s_nop 0
	global_load_lds_dwordx4 v[204:205], off
	s_add_i32 m0, s48, 0x2000
	s_add_u32 s48, s16, 0x4000
	v_lshl_add_u64 v[204:205], s[16:17], 0, v[132:133]
	s_addc_u32 s49, s17, 0
	s_add_i32 s50, s50, s27
	global_load_lds_dwordx4 v[204:205], off
	v_lshl_add_u64 v[204:205], s[48:49], 0, v[136:137]
	s_mov_b32 m0, s50
	v_lshl_add_u64 v[206:207], s[18:19], 0, v[134:135]
	global_load_lds_dwordx4 v[204:205], off
	v_lshl_add_u64 v[204:205], s[48:49], 0, v[132:133]
	s_add_i32 m0, s50, 0x2000
	s_nop 0
	global_load_lds_dwordx4 v[204:205], off
	v_lshl_add_u64 v[204:205], s[18:19], 0, v[138:139]
	s_mov_b32 m0, s28
	s_nop 0
	global_load_lds_dwordx4 v[204:205], off
	s_mov_b32 m0, s29
	s_nop 0
	global_load_lds_dwordx4 v[206:207], off
	ds_read_b128 v[188:191], v159 offset:16384
	ds_read_b128 v[192:195], v159 offset:17408
	ds_read_b128 v[196:199], v159 offset:18432
	ds_read_b128 v[200:203], v159 offset:19456
	ds_read_b128 v[214:217], v159 offset:20480
	ds_read_b128 v[218:221], v159 offset:21504
	ds_read_b128 v[222:225], v159 offset:22528
	ds_read_b128 v[226:229], v159 offset:23552
	s_waitcnt vmcnt(8)
	s_waitcnt lgkmcnt(0)
	s_barrier
	s_setprio 1
	s_waitcnt lgkmcnt(0)
	v_mfma_f32_16x16x32_bf16 v[64:67], v[154:157], v[188:191], v[64:67]
	v_mfma_f32_16x16x32_bf16 v[56:59], v[164:167], v[188:191], v[56:59]
	v_mfma_f32_16x16x32_bf16 v[48:51], v[154:157], v[196:199], v[48:51]
	v_mfma_f32_16x16x32_bf16 v[40:43], v[164:167], v[196:199], v[40:43]
	v_mfma_f32_16x16x32_bf16 v[32:35], v[154:157], v[214:217], v[32:35]
	v_mfma_f32_16x16x32_bf16 v[24:27], v[164:167], v[214:217], v[24:27]
	v_mfma_f32_16x16x32_bf16 v[16:19], v[154:157], v[222:225], v[16:19]
	v_mfma_f32_16x16x32_bf16 v[8:11], v[164:167], v[222:225], v[8:11]
	v_mfma_f32_16x16x32_bf16 v[64:67], v[160:163], v[192:195], v[64:67]
	v_mfma_f32_16x16x32_bf16 v[56:59], v[168:171], v[192:195], v[56:59]
	v_mfma_f32_16x16x32_bf16 v[48:51], v[160:163], v[200:203], v[48:51]
	v_mfma_f32_16x16x32_bf16 v[40:43], v[168:171], v[200:203], v[40:43]
	v_mfma_f32_16x16x32_bf16 v[32:35], v[160:163], v[218:221], v[32:35]
	v_mfma_f32_16x16x32_bf16 v[24:27], v[168:171], v[218:221], v[24:27]
	v_mfma_f32_16x16x32_bf16 v[16:19], v[160:163], v[226:229], v[16:19]
	v_mfma_f32_16x16x32_bf16 v[8:11], v[168:171], v[226:229], v[8:11]
	s_setprio 0
	s_setprio 1
	v_mfma_f32_16x16x32_bf16 v[60:63], v[172:175], v[188:191], v[60:63]
	v_mfma_f32_16x16x32_bf16 v[52:55], v[180:183], v[188:191], v[52:55]
	v_mfma_f32_16x16x32_bf16 v[44:47], v[172:175], v[196:199], v[44:47]
	v_mfma_f32_16x16x32_bf16 v[36:39], v[180:183], v[196:199], v[36:39]
	v_mfma_f32_16x16x32_bf16 v[28:31], v[172:175], v[214:217], v[28:31]
	v_mfma_f32_16x16x32_bf16 v[20:23], v[180:183], v[214:217], v[20:23]
	v_mfma_f32_16x16x32_bf16 v[12:15], v[172:175], v[222:225], v[12:15]
	v_mfma_f32_16x16x32_bf16 v[4:7], v[180:183], v[222:225], v[4:7]
	v_mfma_f32_16x16x32_bf16 v[60:63], v[176:179], v[192:195], v[60:63]
	v_mfma_f32_16x16x32_bf16 v[52:55], v[184:187], v[192:195], v[52:55]
	v_mfma_f32_16x16x32_bf16 v[44:47], v[176:179], v[200:203], v[44:47]
	v_mfma_f32_16x16x32_bf16 v[36:39], v[184:187], v[200:203], v[36:39]
	v_mfma_f32_16x16x32_bf16 v[28:31], v[176:179], v[218:221], v[28:31]
	v_mfma_f32_16x16x32_bf16 v[20:23], v[184:187], v[218:221], v[20:23]
	v_mfma_f32_16x16x32_bf16 v[12:15], v[176:179], v[226:229], v[12:15]
	v_mfma_f32_16x16x32_bf16 v[4:7], v[184:187], v[226:229], v[4:7]
	s_setprio 0
	s_barrier
	s_add_i32 s48, 0, 0x18000
	s_add_i32 s49, 0, 0x1c000
	s_add_u32 s18, s18, 0x80000
	s_addc_u32 s19, s19, 0
	s_mov_b32 m0, s30
	v_lshl_add_u64 v[208:209], s[18:19], 0, v[138:139]
	global_load_lds_dwordx4 v[208:209], off
	v_lshl_add_u64 v[208:209], s[18:19], 0, v[134:135]
	s_mov_b32 m0, s31
	s_nop 0
	global_load_lds_dwordx4 v[208:209], off
	v_add_u32_e32 v168, s48, v158
	v_add_u32_e32 v184, s49, v158
	ds_read_b128 v[154:157], v168
	ds_read_b128 v[160:163], v168 offset:1024
	ds_read_b128 v[164:167], v168 offset:2048
	ds_read_b128 v[168:171], v168 offset:3072
	ds_read_b128 v[172:175], v184
	ds_read_b128 v[176:179], v184 offset:1024
	ds_read_b128 v[180:183], v184 offset:2048
	ds_read_b128 v[184:187], v184 offset:3072
	ds_read_b128 v[188:191], v159 offset:32768
	ds_read_b128 v[192:195], v159 offset:33792
	ds_read_b128 v[196:199], v159 offset:34816
	ds_read_b128 v[200:203], v159 offset:35840
	ds_read_b128 v[214:217], v159 offset:36864
	ds_read_b128 v[218:221], v159 offset:37888
	ds_read_b128 v[222:225], v159 offset:38912
	ds_read_b128 v[226:229], v159 offset:39936
	s_waitcnt vmcnt(8)
	s_waitcnt lgkmcnt(0)
	s_barrier
	s_setprio 1
	s_waitcnt lgkmcnt(0)
	v_mfma_f32_16x16x32_bf16 v[128:131], v[154:157], v[188:191], v[128:131]
	v_mfma_f32_16x16x32_bf16 v[120:123], v[164:167], v[188:191], v[120:123]
	v_mfma_f32_16x16x32_bf16 v[112:115], v[154:157], v[196:199], v[112:115]
	v_mfma_f32_16x16x32_bf16 v[104:107], v[164:167], v[196:199], v[104:107]
	v_mfma_f32_16x16x32_bf16 v[96:99], v[154:157], v[214:217], v[96:99]
	v_mfma_f32_16x16x32_bf16 v[88:91], v[164:167], v[214:217], v[88:91]
	v_mfma_f32_16x16x32_bf16 v[80:83], v[154:157], v[222:225], v[80:83]
	v_mfma_f32_16x16x32_bf16 v[72:75], v[164:167], v[222:225], v[72:75]
	v_mfma_f32_16x16x32_bf16 v[128:131], v[160:163], v[192:195], v[128:131]
	v_mfma_f32_16x16x32_bf16 v[120:123], v[168:171], v[192:195], v[120:123]
	v_mfma_f32_16x16x32_bf16 v[112:115], v[160:163], v[200:203], v[112:115]
	v_mfma_f32_16x16x32_bf16 v[104:107], v[168:171], v[200:203], v[104:107]
	v_mfma_f32_16x16x32_bf16 v[96:99], v[160:163], v[218:221], v[96:99]
	v_mfma_f32_16x16x32_bf16 v[88:91], v[168:171], v[218:221], v[88:91]
	v_mfma_f32_16x16x32_bf16 v[80:83], v[160:163], v[226:229], v[80:83]
	v_mfma_f32_16x16x32_bf16 v[72:75], v[168:171], v[226:229], v[72:75]
	s_setprio 0
	s_setprio 1
	v_mfma_f32_16x16x32_bf16 v[124:127], v[172:175], v[188:191], v[124:127]
	v_mfma_f32_16x16x32_bf16 v[116:119], v[180:183], v[188:191], v[116:119]
	v_mfma_f32_16x16x32_bf16 v[108:111], v[172:175], v[196:199], v[108:111]
	v_mfma_f32_16x16x32_bf16 v[100:103], v[180:183], v[196:199], v[100:103]
	v_mfma_f32_16x16x32_bf16 v[92:95], v[172:175], v[214:217], v[92:95]
	v_mfma_f32_16x16x32_bf16 v[84:87], v[180:183], v[214:217], v[84:87]
	v_mfma_f32_16x16x32_bf16 v[76:79], v[172:175], v[222:225], v[76:79]
	v_mfma_f32_16x16x32_bf16 v[68:71], v[180:183], v[222:225], v[68:71]
	v_mfma_f32_16x16x32_bf16 v[124:127], v[176:179], v[192:195], v[124:127]
	v_mfma_f32_16x16x32_bf16 v[116:119], v[184:187], v[192:195], v[116:119]
	v_mfma_f32_16x16x32_bf16 v[108:111], v[176:179], v[200:203], v[108:111]
	v_mfma_f32_16x16x32_bf16 v[100:103], v[184:187], v[200:203], v[100:103]
	v_mfma_f32_16x16x32_bf16 v[92:95], v[176:179], v[218:221], v[92:95]
	v_mfma_f32_16x16x32_bf16 v[84:87], v[184:187], v[218:221], v[84:87]
	v_mfma_f32_16x16x32_bf16 v[76:79], v[176:179], v[226:229], v[76:79]
	v_mfma_f32_16x16x32_bf16 v[68:71], v[184:187], v[226:229], v[68:71]
	s_setprio 0
	s_barrier
	s_add_u32 s18, s16, 0x8000
	s_addc_u32 s19, s17, 0
	s_add_i32 s48, s48, s27
	v_lshl_add_u64 v[208:209], s[18:19], 0, v[136:137]
	s_mov_b32 m0, s48
	s_nop 0
	global_load_lds_dwordx4 v[208:209], off
	s_add_i32 m0, s48, 0x2000
	s_add_u32 s16, s16, 0xc000
	v_lshl_add_u64 v[208:209], s[18:19], 0, v[132:133]
	s_addc_u32 s17, s17, 0
	s_add_i32 s18, s49, s27
	global_load_lds_dwordx4 v[208:209], off
	v_lshl_add_u64 v[208:209], s[16:17], 0, v[136:137]
	s_mov_b32 m0, s18
	v_lshl_add_u64 v[204:205], v[204:205], 0, s[74:75]
	global_load_lds_dwordx4 v[208:209], off
	v_lshl_add_u64 v[208:209], s[16:17], 0, v[132:133]
	s_add_i32 m0, s18, 0x2000
	s_nop 0
	global_load_lds_dwordx4 v[208:209], off
	s_mov_b32 m0, s38
	s_nop 0
	global_load_lds_dwordx4 v[204:205], off
	v_lshl_add_u64 v[204:205], v[206:207], 0, s[74:75]
	s_mov_b32 m0, s39
	s_nop 0
	global_load_lds_dwordx4 v[204:205], off
	ds_read_b128 v[188:191], v159 offset:49152
	ds_read_b128 v[192:195], v159 offset:50176
	ds_read_b128 v[196:199], v159 offset:51200
	ds_read_b128 v[200:203], v159 offset:52224
	ds_read_b128 v[214:217], v159 offset:53248
	ds_read_b128 v[218:221], v159 offset:54272
	ds_read_b128 v[222:225], v159 offset:55296
	ds_read_b128 v[226:229], v159 offset:56320
	s_waitcnt vmcnt(8)
	s_waitcnt lgkmcnt(0)
	s_barrier
	s_setprio 1
	s_waitcnt lgkmcnt(0)
	v_mfma_f32_16x16x32_bf16 v[64:67], v[154:157], v[188:191], v[64:67]
	v_mfma_f32_16x16x32_bf16 v[56:59], v[164:167], v[188:191], v[56:59]
	v_mfma_f32_16x16x32_bf16 v[48:51], v[154:157], v[196:199], v[48:51]
	v_mfma_f32_16x16x32_bf16 v[40:43], v[164:167], v[196:199], v[40:43]
	v_mfma_f32_16x16x32_bf16 v[32:35], v[154:157], v[214:217], v[32:35]
	v_mfma_f32_16x16x32_bf16 v[24:27], v[164:167], v[214:217], v[24:27]
	v_mfma_f32_16x16x32_bf16 v[16:19], v[154:157], v[222:225], v[16:19]
	v_mfma_f32_16x16x32_bf16 v[8:11], v[164:167], v[222:225], v[8:11]
	v_mfma_f32_16x16x32_bf16 v[64:67], v[160:163], v[192:195], v[64:67]
	v_mfma_f32_16x16x32_bf16 v[56:59], v[168:171], v[192:195], v[56:59]
	v_mfma_f32_16x16x32_bf16 v[48:51], v[160:163], v[200:203], v[48:51]
	v_mfma_f32_16x16x32_bf16 v[40:43], v[168:171], v[200:203], v[40:43]
	v_mfma_f32_16x16x32_bf16 v[32:35], v[160:163], v[218:221], v[32:35]
	v_mfma_f32_16x16x32_bf16 v[24:27], v[168:171], v[218:221], v[24:27]
	v_mfma_f32_16x16x32_bf16 v[16:19], v[160:163], v[226:229], v[16:19]
	v_mfma_f32_16x16x32_bf16 v[8:11], v[168:171], v[226:229], v[8:11]
	s_setprio 0
	s_setprio 1
	v_mfma_f32_16x16x32_bf16 v[60:63], v[172:175], v[188:191], v[60:63]
	v_mfma_f32_16x16x32_bf16 v[52:55], v[180:183], v[188:191], v[52:55]
	v_mfma_f32_16x16x32_bf16 v[44:47], v[172:175], v[196:199], v[44:47]
	v_mfma_f32_16x16x32_bf16 v[36:39], v[180:183], v[196:199], v[36:39]
	v_mfma_f32_16x16x32_bf16 v[28:31], v[172:175], v[214:217], v[28:31]
	v_mfma_f32_16x16x32_bf16 v[20:23], v[180:183], v[214:217], v[20:23]
	v_mfma_f32_16x16x32_bf16 v[12:15], v[172:175], v[222:225], v[12:15]
	v_mfma_f32_16x16x32_bf16 v[4:7], v[180:183], v[222:225], v[4:7]
	v_mfma_f32_16x16x32_bf16 v[60:63], v[176:179], v[192:195], v[60:63]
	v_mfma_f32_16x16x32_bf16 v[52:55], v[184:187], v[192:195], v[52:55]
	v_mfma_f32_16x16x32_bf16 v[44:47], v[176:179], v[200:203], v[44:47]
	v_mfma_f32_16x16x32_bf16 v[36:39], v[184:187], v[200:203], v[36:39]
	v_mfma_f32_16x16x32_bf16 v[28:31], v[176:179], v[218:221], v[28:31]
	v_mfma_f32_16x16x32_bf16 v[20:23], v[184:187], v[218:221], v[20:23]
	v_mfma_f32_16x16x32_bf16 v[12:15], v[176:179], v[226:229], v[12:15]
	v_mfma_f32_16x16x32_bf16 v[4:7], v[184:187], v[226:229], v[4:7]
	s_setprio 0
	s_barrier
	s_add_i32 s47, s47, 2
	s_add_u32 s45, s45, 0x10000
	s_addc_u32 s46, s46, 0
	s_add_u32 s14, s14, 0x100
	s_addc_u32 s15, s15, 0
	s_cmp_gt_u32 s47, 29
	s_cbranch_scc0 .LBB0_160
	s_and_b64 vcc, exec, s[2:3]
	s_cbranch_vccz .LBB0_163
	s_barrier

.LBB0_226:
	s_add_u32 s14, s18, 0x4000
	s_addc_u32 s15, s19, 0
	s_cmpk_eq_i32 s24, 0x54
	s_cselect_b32 s22, s30, s14
	s_cselect_b32 s23, s31, s15
	s_cselect_b32 s20, s38, s2
	s_cselect_b32 s21, s39, s3
	s_add_u32 s14, s22, 0x8000
	s_addc_u32 s15, s23, 0
	s_add_i32 s25, 0, 0x10000
	s_add_i32 s50, 0, 0x14000
	v_lshl_add_u64 v[206:207], s[18:19], 0, v[166:167]
	s_add_i32 m0, s65, 0xc000
	s_nop 0
	global_load_lds_dwordx4 v[206:207], off
	v_lshl_add_u64 v[206:207], s[18:19], 0, v[168:169]
	s_add_i32 m0, s65, 0xe000
	s_nop 0
	global_load_lds_dwordx4 v[206:207], off
	v_add_u32_e32 v144, s25, v174
	v_add_u32_e32 v160, s50, v174
	ds_read_b128 v[132:135], v144
	ds_read_b128 v[136:139], v144 offset:1024
	ds_read_b128 v[140:143], v144 offset:2048
	ds_read_b128 v[144:147], v144 offset:3072
	ds_read_b128 v[148:151], v160
	ds_read_b128 v[152:155], v160 offset:1024
	ds_read_b128 v[156:159], v160 offset:2048
	ds_read_b128 v[160:163], v160 offset:3072
	ds_read_b128 v[170:173], v182
	ds_read_b128 v[186:189], v182 offset:1024
	ds_read_b128 v[190:193], v182 offset:2048
	ds_read_b128 v[194:197], v182 offset:3072
	ds_read_b128 v[198:201], v182 offset:4096
	ds_read_b128 v[202:205], v182 offset:5120
	ds_read_b128 v[214:217], v182 offset:6144
	ds_read_b128 v[218:221], v182 offset:7168
	s_waitcnt vmcnt(8)
	s_waitcnt lgkmcnt(0)
	s_barrier
	s_setprio 1
	s_waitcnt lgkmcnt(0)
	v_mfma_f32_16x16x32_bf16 v[128:131], v[132:135], v[170:173], v[128:131]
	v_mfma_f32_16x16x32_bf16 v[124:127], v[140:143], v[170:173], v[124:127]
	v_mfma_f32_16x16x32_bf16 v[108:111], v[132:135], v[190:193], v[108:111]
	v_mfma_f32_16x16x32_bf16 v[116:119], v[140:143], v[190:193], v[116:119]
	v_mfma_f32_16x16x32_bf16 v[92:95], v[132:135], v[198:201], v[92:95]
	v_mfma_f32_16x16x32_bf16 v[88:91], v[140:143], v[198:201], v[88:91]
	v_mfma_f32_16x16x32_bf16 v[76:79], v[132:135], v[214:217], v[76:79]
	v_mfma_f32_16x16x32_bf16 v[80:83], v[140:143], v[214:217], v[80:83]
	v_mfma_f32_16x16x32_bf16 v[128:131], v[136:139], v[186:189], v[128:131]
	v_mfma_f32_16x16x32_bf16 v[124:127], v[144:147], v[186:189], v[124:127]
	v_mfma_f32_16x16x32_bf16 v[108:111], v[136:139], v[194:197], v[108:111]
	v_mfma_f32_16x16x32_bf16 v[116:119], v[144:147], v[194:197], v[116:119]
	v_mfma_f32_16x16x32_bf16 v[92:95], v[136:139], v[202:205], v[92:95]
	v_mfma_f32_16x16x32_bf16 v[88:91], v[144:147], v[202:205], v[88:91]
	v_mfma_f32_16x16x32_bf16 v[76:79], v[136:139], v[218:221], v[76:79]
	v_mfma_f32_16x16x32_bf16 v[80:83], v[144:147], v[218:221], v[80:83]
	s_setprio 0
	s_setprio 1
	v_mfma_f32_16x16x32_bf16 v[120:123], v[148:151], v[170:173], v[120:123]
	v_mfma_f32_16x16x32_bf16 v[104:107], v[156:159], v[170:173], v[104:107]
	v_mfma_f32_16x16x32_bf16 v[100:103], v[148:151], v[190:193], v[100:103]
	v_mfma_f32_16x16x32_bf16 v[96:99], v[156:159], v[190:193], v[96:99]
	v_mfma_f32_16x16x32_bf16 v[84:87], v[148:151], v[198:201], v[84:87]
	v_mfma_f32_16x16x32_bf16 v[72:75], v[156:159], v[198:201], v[72:75]
	v_mfma_f32_16x16x32_bf16 v[68:71], v[148:151], v[214:217], v[68:71]
	v_mfma_f32_16x16x32_bf16 v[64:67], v[156:159], v[214:217], v[64:67]
	v_mfma_f32_16x16x32_bf16 v[120:123], v[152:155], v[186:189], v[120:123]
	v_mfma_f32_16x16x32_bf16 v[104:107], v[160:163], v[186:189], v[104:107]
	v_mfma_f32_16x16x32_bf16 v[100:103], v[152:155], v[194:197], v[100:103]
	v_mfma_f32_16x16x32_bf16 v[96:99], v[160:163], v[194:197], v[96:99]
	v_mfma_f32_16x16x32_bf16 v[84:87], v[152:155], v[202:205], v[84:87]
	v_mfma_f32_16x16x32_bf16 v[72:75], v[160:163], v[202:205], v[72:75]
	v_mfma_f32_16x16x32_bf16 v[68:71], v[152:155], v[218:221], v[68:71]
	v_mfma_f32_16x16x32_bf16 v[64:67], v[160:163], v[218:221], v[64:67]
	s_setprio 0
	s_barrier
	s_add_i32 s25, s25, s64
	v_lshl_add_u64 v[206:207], s[20:21], 0, v[2:3]
	s_mov_b32 m0, s25
	s_nop 0
	global_load_lds_dwordx4 v[206:207], off
	s_add_i32 m0, s25, 0x2000
	s_add_u32 s26, s20, 0x4000
	v_lshl_add_u64 v[206:207], s[20:21], 0, v[164:165]
	s_addc_u32 s27, s21, 0
	s_add_i32 s25, s50, s64
	global_load_lds_dwordx4 v[206:207], off
	v_lshl_add_u64 v[206:207], s[26:27], 0, v[2:3]
	s_mov_b32 m0, s25
	s_nop 0
	global_load_lds_dwordx4 v[206:207], off
	v_lshl_add_u64 v[206:207], s[26:27], 0, v[164:165]
	s_add_i32 m0, s25, 0x2000
	s_nop 0
	global_load_lds_dwordx4 v[206:207], off
	v_lshl_add_u64 v[206:207], s[22:23], 0, v[2:3]
	s_mov_b32 m0, s65
	s_nop 0
	global_load_lds_dwordx4 v[206:207], off
	v_lshl_add_u64 v[206:207], s[22:23], 0, v[164:165]
	s_mov_b32 m0, s34
	s_nop 0
	global_load_lds_dwordx4 v[206:207], off
	ds_read_b128 v[170:173], v182 offset:16384
	ds_read_b128 v[186:189], v182 offset:17408
	ds_read_b128 v[190:193], v182 offset:18432
	ds_read_b128 v[194:197], v182 offset:19456
	ds_read_b128 v[198:201], v182 offset:20480
	ds_read_b128 v[202:205], v182 offset:21504
	ds_read_b128 v[214:217], v182 offset:22528
	ds_read_b128 v[218:221], v182 offset:23552
	s_waitcnt vmcnt(8)
	s_waitcnt lgkmcnt(0)
	s_barrier
	s_setprio 1
	s_waitcnt lgkmcnt(0)
	v_mfma_f32_16x16x32_bf16 v[60:63], v[132:135], v[170:173], v[60:63]
	v_mfma_f32_16x16x32_bf16 v[56:59], v[140:143], v[170:173], v[56:59]
	v_mfma_f32_16x16x32_bf16 v[44:47], v[132:135], v[190:193], v[44:47]
	v_mfma_f32_16x16x32_bf16 v[48:51], v[140:143], v[190:193], v[48:51]
	v_mfma_f32_16x16x32_bf16 v[28:31], v[132:135], v[198:201], v[28:31]
	v_mfma_f32_16x16x32_bf16 v[24:27], v[140:143], v[198:201], v[24:27]
	v_mfma_f32_16x16x32_bf16 v[112:115], v[132:135], v[214:217], v[112:115]
	v_mfma_f32_16x16x32_bf16 v[16:19], v[140:143], v[214:217], v[16:19]
	v_mfma_f32_16x16x32_bf16 v[60:63], v[136:139], v[186:189], v[60:63]
	v_mfma_f32_16x16x32_bf16 v[56:59], v[144:147], v[186:189], v[56:59]
	v_mfma_f32_16x16x32_bf16 v[44:47], v[136:139], v[194:197], v[44:47]
	v_mfma_f32_16x16x32_bf16 v[48:51], v[144:147], v[194:197], v[48:51]
	v_mfma_f32_16x16x32_bf16 v[28:31], v[136:139], v[202:205], v[28:31]
	v_mfma_f32_16x16x32_bf16 v[24:27], v[144:147], v[202:205], v[24:27]
	v_mfma_f32_16x16x32_bf16 v[112:115], v[136:139], v[218:221], v[112:115]
	v_mfma_f32_16x16x32_bf16 v[16:19], v[144:147], v[218:221], v[16:19]
	s_setprio 0
	s_setprio 1
	v_mfma_f32_16x16x32_bf16 v[52:55], v[148:151], v[170:173], v[52:55]
	v_mfma_f32_16x16x32_bf16 v[40:43], v[156:159], v[170:173], v[40:43]
	v_mfma_f32_16x16x32_bf16 v[36:39], v[148:151], v[190:193], v[36:39]
	v_mfma_f32_16x16x32_bf16 v[32:35], v[156:159], v[190:193], v[32:35]
	v_mfma_f32_16x16x32_bf16 v[20:23], v[148:151], v[198:201], v[20:23]
	v_mfma_f32_16x16x32_bf16 v[12:15], v[156:159], v[198:201], v[12:15]
	v_mfma_f32_16x16x32_bf16 v[4:7], v[148:151], v[214:217], v[4:7]
	v_mfma_f32_16x16x32_bf16 v[8:11], v[156:159], v[214:217], v[8:11]
	v_mfma_f32_16x16x32_bf16 v[52:55], v[152:155], v[186:189], v[52:55]
	v_mfma_f32_16x16x32_bf16 v[40:43], v[160:163], v[186:189], v[40:43]
	v_mfma_f32_16x16x32_bf16 v[36:39], v[152:155], v[194:197], v[36:39]
	v_mfma_f32_16x16x32_bf16 v[32:35], v[160:163], v[194:197], v[32:35]
	v_mfma_f32_16x16x32_bf16 v[20:23], v[152:155], v[202:205], v[20:23]
	v_mfma_f32_16x16x32_bf16 v[12:15], v[160:163], v[202:205], v[12:15]
	v_mfma_f32_16x16x32_bf16 v[4:7], v[152:155], v[218:221], v[4:7]
	v_mfma_f32_16x16x32_bf16 v[8:11], v[160:163], v[218:221], v[8:11]
	s_setprio 0
	s_barrier
	s_add_i32 s25, 0, 0x18000
	s_add_i32 s26, 0, 0x1c000
	s_add_u32 s22, s22, 0x4000
	s_addc_u32 s23, s23, 0
	s_mov_b32 m0, s35
	v_lshl_add_u64 v[206:207], s[22:23], 0, v[2:3]
	global_load_lds_dwordx4 v[206:207], off
	v_lshl_add_u64 v[206:207], s[22:23], 0, v[164:165]
	s_mov_b32 m0, s40
	s_nop 0
	global_load_lds_dwordx4 v[206:207], off
	v_add_u32_e32 v144, s25, v174
	v_add_u32_e32 v160, s26, v174
	ds_read_b128 v[132:135], v144
	ds_read_b128 v[136:139], v144 offset:1024
	ds_read_b128 v[140:143], v144 offset:2048
	ds_read_b128 v[144:147], v144 offset:3072
	ds_read_b128 v[148:151], v160
	ds_read_b128 v[152:155], v160 offset:1024
	ds_read_b128 v[156:159], v160 offset:2048
	ds_read_b128 v[160:163], v160 offset:3072
	ds_read_b128 v[170:173], v182 offset:32768
	ds_read_b128 v[186:189], v182 offset:33792
	ds_read_b128 v[190:193], v182 offset:34816
	ds_read_b128 v[194:197], v182 offset:35840
	ds_read_b128 v[198:201], v182 offset:36864
	ds_read_b128 v[202:205], v182 offset:37888
	ds_read_b128 v[214:217], v182 offset:38912
	ds_read_b128 v[218:221], v182 offset:39936
	s_waitcnt vmcnt(8)
	s_waitcnt lgkmcnt(0)
	s_barrier
	s_setprio 1
	s_waitcnt lgkmcnt(0)
	v_mfma_f32_16x16x32_bf16 v[128:131], v[132:135], v[170:173], v[128:131]
	v_mfma_f32_16x16x32_bf16 v[124:127], v[140:143], v[170:173], v[124:127]
	v_mfma_f32_16x16x32_bf16 v[108:111], v[132:135], v[190:193], v[108:111]
	v_mfma_f32_16x16x32_bf16 v[116:119], v[140:143], v[190:193], v[116:119]
	v_mfma_f32_16x16x32_bf16 v[92:95], v[132:135], v[198:201], v[92:95]
	v_mfma_f32_16x16x32_bf16 v[88:91], v[140:143], v[198:201], v[88:91]
	v_mfma_f32_16x16x32_bf16 v[76:79], v[132:135], v[214:217], v[76:79]
	v_mfma_f32_16x16x32_bf16 v[80:83], v[140:143], v[214:217], v[80:83]
	v_mfma_f32_16x16x32_bf16 v[128:131], v[136:139], v[186:189], v[128:131]
	v_mfma_f32_16x16x32_bf16 v[124:127], v[144:147], v[186:189], v[124:127]
	v_mfma_f32_16x16x32_bf16 v[108:111], v[136:139], v[194:197], v[108:111]
	v_mfma_f32_16x16x32_bf16 v[116:119], v[144:147], v[194:197], v[116:119]
	v_mfma_f32_16x16x32_bf16 v[92:95], v[136:139], v[202:205], v[92:95]
	v_mfma_f32_16x16x32_bf16 v[88:91], v[144:147], v[202:205], v[88:91]
	v_mfma_f32_16x16x32_bf16 v[76:79], v[136:139], v[218:221], v[76:79]
	v_mfma_f32_16x16x32_bf16 v[80:83], v[144:147], v[218:221], v[80:83]
	s_setprio 0
	s_setprio 1
	v_mfma_f32_16x16x32_bf16 v[120:123], v[148:151], v[170:173], v[120:123]
	v_mfma_f32_16x16x32_bf16 v[104:107], v[156:159], v[170:173], v[104:107]
	v_mfma_f32_16x16x32_bf16 v[100:103], v[148:151], v[190:193], v[100:103]
	v_mfma_f32_16x16x32_bf16 v[96:99], v[156:159], v[190:193], v[96:99]
	v_mfma_f32_16x16x32_bf16 v[84:87], v[148:151], v[198:201], v[84:87]
	v_mfma_f32_16x16x32_bf16 v[72:75], v[156:159], v[198:201], v[72:75]
	v_mfma_f32_16x16x32_bf16 v[68:71], v[148:151], v[214:217], v[68:71]
	v_mfma_f32_16x16x32_bf16 v[64:67], v[156:159], v[214:217], v[64:67]
	v_mfma_f32_16x16x32_bf16 v[120:123], v[152:155], v[186:189], v[120:123]
	v_mfma_f32_16x16x32_bf16 v[104:107], v[160:163], v[186:189], v[104:107]
	v_mfma_f32_16x16x32_bf16 v[100:103], v[152:155], v[194:197], v[100:103]
	v_mfma_f32_16x16x32_bf16 v[96:99], v[160:163], v[194:197], v[96:99]
	v_mfma_f32_16x16x32_bf16 v[84:87], v[152:155], v[202:205], v[84:87]
	v_mfma_f32_16x16x32_bf16 v[72:75], v[160:163], v[202:205], v[72:75]
	v_mfma_f32_16x16x32_bf16 v[68:71], v[152:155], v[218:221], v[68:71]
	v_mfma_f32_16x16x32_bf16 v[64:67], v[160:163], v[218:221], v[64:67]
	s_setprio 0
	s_barrier
	s_add_u32 s22, s20, 0x8000
	s_addc_u32 s23, s21, 0
	s_add_i32 s25, s25, s64
	v_lshl_add_u64 v[206:207], s[22:23], 0, v[2:3]
	s_mov_b32 m0, s25
	s_nop 0
	global_load_lds_dwordx4 v[206:207], off
	s_add_i32 m0, s25, 0x2000
	s_add_u32 s20, s20, 0xc000
	v_lshl_add_u64 v[206:207], s[22:23], 0, v[164:165]
	s_addc_u32 s21, s21, 0
	s_add_i32 s22, s26, s64
	global_load_lds_dwordx4 v[206:207], off
	v_lshl_add_u64 v[206:207], s[20:21], 0, v[2:3]
	s_mov_b32 m0, s22
	s_nop 0
	global_load_lds_dwordx4 v[206:207], off
	v_lshl_add_u64 v[206:207], s[20:21], 0, v[164:165]
	s_add_i32 m0, s22, 0x2000
	s_nop 0
	global_load_lds_dwordx4 v[206:207], off
	v_lshl_add_u64 v[206:207], s[14:15], 0, v[2:3]
	s_mov_b32 m0, s41
	s_nop 0
	global_load_lds_dwordx4 v[206:207], off
	v_lshl_add_u64 v[206:207], s[14:15], 0, v[164:165]
	s_mov_b32 m0, s46
	s_nop 0
	global_load_lds_dwordx4 v[206:207], off
	ds_read_b128 v[170:173], v182 offset:49152
	ds_read_b128 v[186:189], v182 offset:50176
	ds_read_b128 v[190:193], v182 offset:51200
	ds_read_b128 v[194:197], v182 offset:52224
	ds_read_b128 v[198:201], v182 offset:53248
	ds_read_b128 v[202:205], v182 offset:54272
	ds_read_b128 v[214:217], v182 offset:55296
	ds_read_b128 v[218:221], v182 offset:56320
	s_waitcnt vmcnt(8)
	s_waitcnt lgkmcnt(0)
	s_barrier
	s_setprio 1
	s_waitcnt lgkmcnt(0)
	v_mfma_f32_16x16x32_bf16 v[60:63], v[132:135], v[170:173], v[60:63]
	v_mfma_f32_16x16x32_bf16 v[56:59], v[140:143], v[170:173], v[56:59]
	v_mfma_f32_16x16x32_bf16 v[44:47], v[132:135], v[190:193], v[44:47]
	v_mfma_f32_16x16x32_bf16 v[48:51], v[140:143], v[190:193], v[48:51]
	v_mfma_f32_16x16x32_bf16 v[28:31], v[132:135], v[198:201], v[28:31]
	v_mfma_f32_16x16x32_bf16 v[24:27], v[140:143], v[198:201], v[24:27]
	v_mfma_f32_16x16x32_bf16 v[112:115], v[132:135], v[214:217], v[112:115]
	v_mfma_f32_16x16x32_bf16 v[16:19], v[140:143], v[214:217], v[16:19]
	v_mfma_f32_16x16x32_bf16 v[60:63], v[136:139], v[186:189], v[60:63]
	v_mfma_f32_16x16x32_bf16 v[56:59], v[144:147], v[186:189], v[56:59]
	v_mfma_f32_16x16x32_bf16 v[44:47], v[136:139], v[194:197], v[44:47]
	v_mfma_f32_16x16x32_bf16 v[48:51], v[144:147], v[194:197], v[48:51]
	v_mfma_f32_16x16x32_bf16 v[28:31], v[136:139], v[202:205], v[28:31]
	v_mfma_f32_16x16x32_bf16 v[24:27], v[144:147], v[202:205], v[24:27]
	v_mfma_f32_16x16x32_bf16 v[112:115], v[136:139], v[218:221], v[112:115]
	v_mfma_f32_16x16x32_bf16 v[16:19], v[144:147], v[218:221], v[16:19]
	s_setprio 0
	s_setprio 1
	v_mfma_f32_16x16x32_bf16 v[52:55], v[148:151], v[170:173], v[52:55]
	v_mfma_f32_16x16x32_bf16 v[40:43], v[156:159], v[170:173], v[40:43]
	v_mfma_f32_16x16x32_bf16 v[36:39], v[148:151], v[190:193], v[36:39]
	v_mfma_f32_16x16x32_bf16 v[32:35], v[156:159], v[190:193], v[32:35]
	v_mfma_f32_16x16x32_bf16 v[20:23], v[148:151], v[198:201], v[20:23]
	v_mfma_f32_16x16x32_bf16 v[12:15], v[156:159], v[198:201], v[12:15]
	v_mfma_f32_16x16x32_bf16 v[4:7], v[148:151], v[214:217], v[4:7]
	v_mfma_f32_16x16x32_bf16 v[8:11], v[156:159], v[214:217], v[8:11]
	v_mfma_f32_16x16x32_bf16 v[52:55], v[152:155], v[186:189], v[52:55]
	v_mfma_f32_16x16x32_bf16 v[40:43], v[160:163], v[186:189], v[40:43]
	v_mfma_f32_16x16x32_bf16 v[36:39], v[152:155], v[194:197], v[36:39]
	v_mfma_f32_16x16x32_bf16 v[32:35], v[160:163], v[194:197], v[32:35]
	v_mfma_f32_16x16x32_bf16 v[20:23], v[152:155], v[202:205], v[20:23]
	v_mfma_f32_16x16x32_bf16 v[12:15], v[160:163], v[202:205], v[12:15]
	v_mfma_f32_16x16x32_bf16 v[4:7], v[152:155], v[218:221], v[4:7]
	v_mfma_f32_16x16x32_bf16 v[8:11], v[160:163], v[218:221], v[8:11]
	s_setprio 0
	s_barrier
	s_add_i32 s24, s24, 2
	s_add_u32 s18, s18, 0x10000
	s_addc_u32 s19, s19, 0
	s_add_u32 s2, s2, 0x10000
	s_addc_u32 s3, s3, 0
	s_cmpk_gt_u32 s24, 0x55
	s_cbranch_scc0 .LBB0_226
	v_readlane_b32 s2, v254, 46
	v_readlane_b32 s3, v254, 47
	s_and_b64 vcc, exec, s[2:3]
	s_cbranch_vccz .LBB0_229
	s_barrier

.LBB0_338:
	s_add_u32 s22, s12, 0xfff80080
	s_addc_u32 s23, s13, -1
	s_add_i32 s52, 0, 0x10000
	s_cmp_eq_u32 s51, 28
	s_cselect_b32 s25, s5, s23
	s_cselect_b32 s24, s15, s22
	s_cselect_b32 s23, s7, s50
	s_cselect_b32 s22, s26, s27
	s_add_i32 s54, 0, 0x14000
	v_lshl_add_u64 v[206:207], s[12:13], 0, v[220:221]
	s_add_i32 m0, s19, 0xc000
	s_nop 0
	global_load_lds_dwordx4 v[206:207], off
	v_lshl_add_u64 v[206:207], s[12:13], 0, v[222:223]
	s_add_i32 m0, s19, 0xe000
	s_nop 0
	global_load_lds_dwordx4 v[206:207], off
	v_add_u32_e32 v2, s52, v205
	ds_read_b128 v[92:95], v2
	ds_read_b128 v[96:99], v2 offset:1024
	ds_read_b128 v[120:123], v2 offset:2048
	ds_read_b128 v[132:135], v2 offset:3072
	v_add_u32_e32 v2, s54, v205
	ds_read_b128 v[140:143], v2
	ds_read_b128 v[152:155], v2 offset:1024
	ds_read_b128 v[156:159], v2 offset:2048
	ds_read_b128 v[160:163], v2 offset:3072
	ds_read_b128 v[164:167], v215
	ds_read_b128 v[168:171], v215 offset:1024
	ds_read_b128 v[172:175], v215 offset:2048
	ds_read_b128 v[176:179], v215 offset:3072
	ds_read_b128 v[180:183], v215 offset:4096
	ds_read_b128 v[184:187], v215 offset:5120
	ds_read_b128 v[188:191], v215 offset:6144
	ds_read_b128 v[192:195], v215 offset:7168
	s_waitcnt vmcnt(8)
	s_waitcnt lgkmcnt(0)
	s_barrier
	s_setprio 1
	s_waitcnt lgkmcnt(0)
	v_mfma_f32_16x16x32_bf16 v[148:151], v[92:95], v[164:167], v[148:151]
	v_mfma_f32_16x16x32_bf16 v[144:147], v[120:123], v[164:167], v[144:147]
	v_mfma_f32_16x16x32_bf16 v[124:127], v[92:95], v[172:175], v[124:127]
	v_mfma_f32_16x16x32_bf16 v[116:119], v[120:123], v[172:175], v[116:119]
	v_mfma_f32_16x16x32_bf16 v[104:107], v[92:95], v[180:183], v[104:107]
	v_mfma_f32_16x16x32_bf16 v[100:103], v[120:123], v[180:183], v[100:103]
	v_mfma_f32_16x16x32_bf16 v[80:83], v[92:95], v[188:191], v[80:83]
	v_mfma_f32_16x16x32_bf16 v[76:79], v[120:123], v[188:191], v[76:79]
	v_mfma_f32_16x16x32_bf16 v[148:151], v[96:99], v[168:171], v[148:151]
	v_mfma_f32_16x16x32_bf16 v[144:147], v[132:135], v[168:171], v[144:147]
	v_mfma_f32_16x16x32_bf16 v[124:127], v[96:99], v[176:179], v[124:127]
	v_mfma_f32_16x16x32_bf16 v[116:119], v[132:135], v[176:179], v[116:119]
	v_mfma_f32_16x16x32_bf16 v[104:107], v[96:99], v[184:187], v[104:107]
	v_mfma_f32_16x16x32_bf16 v[100:103], v[132:135], v[184:187], v[100:103]
	v_mfma_f32_16x16x32_bf16 v[80:83], v[96:99], v[192:195], v[80:83]
	v_mfma_f32_16x16x32_bf16 v[76:79], v[132:135], v[192:195], v[76:79]
	s_setprio 0
	s_setprio 1
	v_mfma_f32_16x16x32_bf16 v[136:139], v[140:143], v[164:167], v[136:139]
	v_mfma_f32_16x16x32_bf16 v[128:131], v[156:159], v[164:167], v[128:131]
	v_mfma_f32_16x16x32_bf16 v[112:115], v[140:143], v[172:175], v[112:115]
	v_mfma_f32_16x16x32_bf16 v[108:111], v[156:159], v[172:175], v[108:111]
	v_mfma_f32_16x16x32_bf16 v[88:91], v[140:143], v[180:183], v[88:91]
	v_mfma_f32_16x16x32_bf16 v[84:87], v[156:159], v[180:183], v[84:87]
	v_mfma_f32_16x16x32_bf16 v[72:75], v[140:143], v[188:191], v[72:75]
	v_mfma_f32_16x16x32_bf16 v[68:71], v[156:159], v[188:191], v[68:71]
	v_mfma_f32_16x16x32_bf16 v[136:139], v[152:155], v[168:171], v[136:139]
	v_mfma_f32_16x16x32_bf16 v[128:131], v[160:163], v[168:171], v[128:131]
	v_mfma_f32_16x16x32_bf16 v[112:115], v[152:155], v[176:179], v[112:115]
	v_mfma_f32_16x16x32_bf16 v[108:111], v[160:163], v[176:179], v[108:111]
	v_mfma_f32_16x16x32_bf16 v[88:91], v[152:155], v[184:187], v[88:91]
	v_mfma_f32_16x16x32_bf16 v[84:87], v[160:163], v[184:187], v[84:87]
	v_mfma_f32_16x16x32_bf16 v[72:75], v[152:155], v[192:195], v[72:75]
	v_mfma_f32_16x16x32_bf16 v[68:71], v[160:163], v[192:195], v[68:71]
	s_setprio 0
	s_barrier
	s_add_i32 s52, s52, s37
	v_lshl_add_u64 v[206:207], s[22:23], 0, v[198:199]
	s_mov_b32 m0, s52
	s_nop 0
	global_load_lds_dwordx4 v[206:207], off
	s_add_i32 m0, s52, 0x2000
	s_add_u32 s52, s22, 0x4000
	v_lshl_add_u64 v[206:207], s[22:23], 0, v[202:203]
	s_addc_u32 s53, s23, 0
	s_add_i32 s54, s54, s37
	global_load_lds_dwordx4 v[206:207], off
	v_lshl_add_u64 v[206:207], s[52:53], 0, v[198:199]
	s_mov_b32 m0, s54
	v_lshl_add_u64 v[208:209], s[24:25], 0, v[200:201]
	global_load_lds_dwordx4 v[206:207], off
	v_lshl_add_u64 v[206:207], s[52:53], 0, v[202:203]
	s_add_i32 m0, s54, 0x2000
	s_nop 0
	global_load_lds_dwordx4 v[206:207], off
	v_lshl_add_u64 v[206:207], s[24:25], 0, v[196:197]
	s_mov_b32 m0, s19
	s_nop 0
	global_load_lds_dwordx4 v[206:207], off
	s_mov_b32 m0, s38
	s_nop 0
	global_load_lds_dwordx4 v[208:209], off
	ds_read_b128 v[164:167], v215 offset:16384
	ds_read_b128 v[168:171], v215 offset:17408
	ds_read_b128 v[172:175], v215 offset:18432
	ds_read_b128 v[176:179], v215 offset:19456
	ds_read_b128 v[180:183], v215 offset:20480
	ds_read_b128 v[184:187], v215 offset:21504
	ds_read_b128 v[188:191], v215 offset:22528
	ds_read_b128 v[192:195], v215 offset:23552
	s_waitcnt vmcnt(8)
	s_waitcnt lgkmcnt(0)
	s_barrier
	s_setprio 1
	s_waitcnt lgkmcnt(0)
	v_mfma_f32_16x16x32_bf16 v[64:67], v[92:95], v[164:167], v[64:67]
	v_mfma_f32_16x16x32_bf16 v[60:63], v[120:123], v[164:167], v[60:63]
	v_mfma_f32_16x16x32_bf16 v[48:51], v[92:95], v[172:175], v[48:51]
	v_mfma_f32_16x16x32_bf16 v[44:47], v[120:123], v[172:175], v[44:47]
	v_mfma_f32_16x16x32_bf16 v[32:35], v[92:95], v[180:183], v[32:35]
	v_mfma_f32_16x16x32_bf16 v[28:31], v[120:123], v[180:183], v[28:31]
	v_mfma_f32_16x16x32_bf16 v[16:19], v[92:95], v[188:191], v[16:19]
	v_mfma_f32_16x16x32_bf16 v[12:15], v[120:123], v[188:191], v[12:15]
	v_mfma_f32_16x16x32_bf16 v[64:67], v[96:99], v[168:171], v[64:67]
	v_mfma_f32_16x16x32_bf16 v[60:63], v[132:135], v[168:171], v[60:63]
	v_mfma_f32_16x16x32_bf16 v[48:51], v[96:99], v[176:179], v[48:51]
	v_mfma_f32_16x16x32_bf16 v[44:47], v[132:135], v[176:179], v[44:47]
	v_mfma_f32_16x16x32_bf16 v[32:35], v[96:99], v[184:187], v[32:35]
	v_mfma_f32_16x16x32_bf16 v[28:31], v[132:135], v[184:187], v[28:31]
	v_mfma_f32_16x16x32_bf16 v[16:19], v[96:99], v[192:195], v[16:19]
	v_mfma_f32_16x16x32_bf16 v[12:15], v[132:135], v[192:195], v[12:15]
	s_setprio 0
	s_setprio 1
	v_mfma_f32_16x16x32_bf16 v[56:59], v[140:143], v[164:167], v[56:59]
	v_mfma_f32_16x16x32_bf16 v[52:55], v[156:159], v[164:167], v[52:55]
	v_mfma_f32_16x16x32_bf16 v[40:43], v[140:143], v[172:175], v[40:43]
	v_mfma_f32_16x16x32_bf16 v[36:39], v[156:159], v[172:175], v[36:39]
	v_mfma_f32_16x16x32_bf16 v[24:27], v[140:143], v[180:183], v[24:27]
	v_mfma_f32_16x16x32_bf16 v[20:23], v[156:159], v[180:183], v[20:23]
	v_mfma_f32_16x16x32_bf16 v[8:11], v[140:143], v[188:191], v[8:11]
	v_mfma_f32_16x16x32_bf16 v[4:7], v[156:159], v[188:191], v[4:7]
	v_mfma_f32_16x16x32_bf16 v[56:59], v[152:155], v[168:171], v[56:59]
	v_mfma_f32_16x16x32_bf16 v[52:55], v[160:163], v[168:171], v[52:55]
	v_mfma_f32_16x16x32_bf16 v[40:43], v[152:155], v[176:179], v[40:43]
	v_mfma_f32_16x16x32_bf16 v[36:39], v[160:163], v[176:179], v[36:39]
	v_mfma_f32_16x16x32_bf16 v[24:27], v[152:155], v[184:187], v[24:27]
	v_mfma_f32_16x16x32_bf16 v[20:23], v[160:163], v[184:187], v[20:23]
	v_mfma_f32_16x16x32_bf16 v[8:11], v[152:155], v[192:195], v[8:11]
	v_mfma_f32_16x16x32_bf16 v[4:7], v[160:163], v[192:195], v[4:7]
	s_setprio 0
	s_barrier
	s_add_i32 s52, 0, 0x18000
	s_add_i32 s53, 0, 0x1c000
	s_add_u32 s24, s24, 0x80000
	s_addc_u32 s25, s25, 0
	s_mov_b32 m0, s39
	v_lshl_add_u64 v[210:211], s[24:25], 0, v[196:197]
	global_load_lds_dwordx4 v[210:211], off
	v_lshl_add_u64 v[210:211], s[24:25], 0, v[200:201]
	s_mov_b32 m0, s40
	s_nop 0
	global_load_lds_dwordx4 v[210:211], off
	v_add_u32_e32 v2, s52, v205
	ds_read_b128 v[92:95], v2
	ds_read_b128 v[96:99], v2 offset:1024
	ds_read_b128 v[120:123], v2 offset:2048
	ds_read_b128 v[132:135], v2 offset:3072
	v_add_u32_e32 v2, s53, v205
	ds_read_b128 v[140:143], v2
	ds_read_b128 v[152:155], v2 offset:1024
	ds_read_b128 v[156:159], v2 offset:2048
	ds_read_b128 v[160:163], v2 offset:3072
	ds_read_b128 v[164:167], v215 offset:32768
	ds_read_b128 v[168:171], v215 offset:33792
	ds_read_b128 v[172:175], v215 offset:34816
	ds_read_b128 v[176:179], v215 offset:35840
	ds_read_b128 v[180:183], v215 offset:36864
	ds_read_b128 v[184:187], v215 offset:37888
	ds_read_b128 v[188:191], v215 offset:38912
	ds_read_b128 v[192:195], v215 offset:39936
	s_waitcnt vmcnt(8)
	s_waitcnt lgkmcnt(0)
	s_barrier
	s_setprio 1
	s_waitcnt lgkmcnt(0)
	v_mfma_f32_16x16x32_bf16 v[148:151], v[92:95], v[164:167], v[148:151]
	v_mfma_f32_16x16x32_bf16 v[144:147], v[120:123], v[164:167], v[144:147]
	v_mfma_f32_16x16x32_bf16 v[124:127], v[92:95], v[172:175], v[124:127]
	v_mfma_f32_16x16x32_bf16 v[116:119], v[120:123], v[172:175], v[116:119]
	v_mfma_f32_16x16x32_bf16 v[104:107], v[92:95], v[180:183], v[104:107]
	v_mfma_f32_16x16x32_bf16 v[100:103], v[120:123], v[180:183], v[100:103]
	v_mfma_f32_16x16x32_bf16 v[80:83], v[92:95], v[188:191], v[80:83]
	v_mfma_f32_16x16x32_bf16 v[76:79], v[120:123], v[188:191], v[76:79]
	v_mfma_f32_16x16x32_bf16 v[148:151], v[96:99], v[168:171], v[148:151]
	v_mfma_f32_16x16x32_bf16 v[144:147], v[132:135], v[168:171], v[144:147]
	v_mfma_f32_16x16x32_bf16 v[124:127], v[96:99], v[176:179], v[124:127]
	v_mfma_f32_16x16x32_bf16 v[116:119], v[132:135], v[176:179], v[116:119]
	v_mfma_f32_16x16x32_bf16 v[104:107], v[96:99], v[184:187], v[104:107]
	v_mfma_f32_16x16x32_bf16 v[100:103], v[132:135], v[184:187], v[100:103]
	v_mfma_f32_16x16x32_bf16 v[80:83], v[96:99], v[192:195], v[80:83]
	v_mfma_f32_16x16x32_bf16 v[76:79], v[132:135], v[192:195], v[76:79]
	s_setprio 0
	s_setprio 1
	v_mfma_f32_16x16x32_bf16 v[136:139], v[140:143], v[164:167], v[136:139]
	v_mfma_f32_16x16x32_bf16 v[128:131], v[156:159], v[164:167], v[128:131]
	v_mfma_f32_16x16x32_bf16 v[112:115], v[140:143], v[172:175], v[112:115]
	v_mfma_f32_16x16x32_bf16 v[108:111], v[156:159], v[172:175], v[108:111]
	v_mfma_f32_16x16x32_bf16 v[88:91], v[140:143], v[180:183], v[88:91]
	v_mfma_f32_16x16x32_bf16 v[84:87], v[156:159], v[180:183], v[84:87]
	v_mfma_f32_16x16x32_bf16 v[72:75], v[140:143], v[188:191], v[72:75]
	v_mfma_f32_16x16x32_bf16 v[68:71], v[156:159], v[188:191], v[68:71]
	v_mfma_f32_16x16x32_bf16 v[136:139], v[152:155], v[168:171], v[136:139]
	v_mfma_f32_16x16x32_bf16 v[128:131], v[160:163], v[168:171], v[128:131]
	v_mfma_f32_16x16x32_bf16 v[112:115], v[152:155], v[176:179], v[112:115]
	v_mfma_f32_16x16x32_bf16 v[108:111], v[160:163], v[176:179], v[108:111]
	v_mfma_f32_16x16x32_bf16 v[88:91], v[152:155], v[184:187], v[88:91]
	v_mfma_f32_16x16x32_bf16 v[84:87], v[160:163], v[184:187], v[84:87]
	v_mfma_f32_16x16x32_bf16 v[72:75], v[152:155], v[192:195], v[72:75]
	v_mfma_f32_16x16x32_bf16 v[68:71], v[160:163], v[192:195], v[68:71]
	s_setprio 0
	s_barrier
	s_add_u32 s24, s22, 0x8000
	s_addc_u32 s25, s23, 0
	s_add_i32 s52, s52, s37
	v_lshl_add_u64 v[210:211], s[24:25], 0, v[198:199]
	s_mov_b32 m0, s52
	s_nop 0
	global_load_lds_dwordx4 v[210:211], off
	s_add_i32 m0, s52, 0x2000
	s_add_u32 s22, s22, 0xc000
	v_lshl_add_u64 v[210:211], s[24:25], 0, v[202:203]
	s_addc_u32 s23, s23, 0
	s_add_i32 s24, s53, s37
	global_load_lds_dwordx4 v[210:211], off
	v_lshl_add_u64 v[210:211], s[22:23], 0, v[198:199]
	s_mov_b32 m0, s24
	v_lshl_add_u64 v[206:207], v[206:207], 0, s[74:75]
	global_load_lds_dwordx4 v[210:211], off
	v_lshl_add_u64 v[210:211], s[22:23], 0, v[202:203]
	s_add_i32 m0, s24, 0x2000
	s_nop 0
	global_load_lds_dwordx4 v[210:211], off
	s_mov_b32 m0, s47
	s_nop 0
	global_load_lds_dwordx4 v[206:207], off
	v_lshl_add_u64 v[206:207], v[208:209], 0, s[74:75]
	s_mov_b32 m0, s48
	s_nop 0
	global_load_lds_dwordx4 v[206:207], off
	ds_read_b128 v[164:167], v215 offset:49152
	ds_read_b128 v[168:171], v215 offset:50176
	ds_read_b128 v[172:175], v215 offset:51200
	ds_read_b128 v[176:179], v215 offset:52224
	ds_read_b128 v[180:183], v215 offset:53248
	ds_read_b128 v[184:187], v215 offset:54272
	ds_read_b128 v[188:191], v215 offset:55296
	ds_read_b128 v[192:195], v215 offset:56320
	s_waitcnt vmcnt(8)
	s_waitcnt lgkmcnt(0)
	s_barrier
	s_setprio 1
	s_waitcnt lgkmcnt(0)
	v_mfma_f32_16x16x32_bf16 v[64:67], v[92:95], v[164:167], v[64:67]
	v_mfma_f32_16x16x32_bf16 v[60:63], v[120:123], v[164:167], v[60:63]
	v_mfma_f32_16x16x32_bf16 v[48:51], v[92:95], v[172:175], v[48:51]
	v_mfma_f32_16x16x32_bf16 v[44:47], v[120:123], v[172:175], v[44:47]
	v_mfma_f32_16x16x32_bf16 v[32:35], v[92:95], v[180:183], v[32:35]
	v_mfma_f32_16x16x32_bf16 v[28:31], v[120:123], v[180:183], v[28:31]
	v_mfma_f32_16x16x32_bf16 v[16:19], v[92:95], v[188:191], v[16:19]
	v_mfma_f32_16x16x32_bf16 v[12:15], v[120:123], v[188:191], v[12:15]
	v_mfma_f32_16x16x32_bf16 v[64:67], v[96:99], v[168:171], v[64:67]
	v_mfma_f32_16x16x32_bf16 v[60:63], v[132:135], v[168:171], v[60:63]
	v_mfma_f32_16x16x32_bf16 v[48:51], v[96:99], v[176:179], v[48:51]
	v_mfma_f32_16x16x32_bf16 v[44:47], v[132:135], v[176:179], v[44:47]
	v_mfma_f32_16x16x32_bf16 v[32:35], v[96:99], v[184:187], v[32:35]
	v_mfma_f32_16x16x32_bf16 v[28:31], v[132:135], v[184:187], v[28:31]
	v_mfma_f32_16x16x32_bf16 v[16:19], v[96:99], v[192:195], v[16:19]
	v_mfma_f32_16x16x32_bf16 v[12:15], v[132:135], v[192:195], v[12:15]
	s_setprio 0
	s_setprio 1
	v_mfma_f32_16x16x32_bf16 v[56:59], v[140:143], v[164:167], v[56:59]
	v_mfma_f32_16x16x32_bf16 v[52:55], v[156:159], v[164:167], v[52:55]
	v_mfma_f32_16x16x32_bf16 v[40:43], v[140:143], v[172:175], v[40:43]
	v_mfma_f32_16x16x32_bf16 v[36:39], v[156:159], v[172:175], v[36:39]
	v_mfma_f32_16x16x32_bf16 v[24:27], v[140:143], v[180:183], v[24:27]
	v_mfma_f32_16x16x32_bf16 v[20:23], v[156:159], v[180:183], v[20:23]
	v_mfma_f32_16x16x32_bf16 v[8:11], v[140:143], v[188:191], v[8:11]
	v_mfma_f32_16x16x32_bf16 v[4:7], v[156:159], v[188:191], v[4:7]
	v_mfma_f32_16x16x32_bf16 v[56:59], v[152:155], v[168:171], v[56:59]
	v_mfma_f32_16x16x32_bf16 v[52:55], v[160:163], v[168:171], v[52:55]
	v_mfma_f32_16x16x32_bf16 v[40:43], v[152:155], v[176:179], v[40:43]
	v_mfma_f32_16x16x32_bf16 v[36:39], v[160:163], v[176:179], v[36:39]
	v_mfma_f32_16x16x32_bf16 v[24:27], v[152:155], v[184:187], v[24:27]
	v_mfma_f32_16x16x32_bf16 v[20:23], v[160:163], v[184:187], v[20:23]
	v_mfma_f32_16x16x32_bf16 v[8:11], v[152:155], v[192:195], v[8:11]
	v_mfma_f32_16x16x32_bf16 v[4:7], v[160:163], v[192:195], v[4:7]
	s_setprio 0
	s_barrier
	s_add_i32 s51, s51, 2
	s_add_u32 s27, s27, 0x10000
	s_addc_u32 s50, s50, 0
	s_add_u32 s12, s12, 0x100
	s_addc_u32 s13, s13, 0
	s_cmp_gt_u32 s51, 29
	s_cbranch_scc0 .LBB0_338
	s_and_b64 vcc, exec, s[2:3]
	s_cbranch_vccz .LBB0_341
	s_barrier

.LBB0_640:
	s_add_u32 s22, s20, 0xfff80080
	s_addc_u32 s23, s21, -1
	s_add_i32 s55, 0, 0x10000
	s_cmp_eq_u32 s54, 28
	s_cselect_b32 s25, s5, s23
	s_cselect_b32 s24, s19, s22
	s_cselect_b32 s23, s26, s49
	s_cselect_b32 s22, s27, s29
	s_add_i32 s63, 0, 0x14000
	v_lshl_add_u64 v[206:207], s[20:21], 0, v[170:171]
	s_add_i32 m0, s39, 0xc000
	s_nop 0
	global_load_lds_dwordx4 v[206:207], off
	v_lshl_add_u64 v[206:207], s[20:21], 0, v[172:173]
	s_add_i32 m0, s39, 0xe000
	s_nop 0
	global_load_lds_dwordx4 v[206:207], off
	v_add_u32_e32 v144, s55, v178
	v_add_u32_e32 v160, s63, v178
	ds_read_b128 v[132:135], v144
	ds_read_b128 v[136:139], v144 offset:1024
	ds_read_b128 v[140:143], v144 offset:2048
	ds_read_b128 v[144:147], v144 offset:3072
	ds_read_b128 v[148:151], v160
	ds_read_b128 v[152:155], v160 offset:1024
	ds_read_b128 v[156:159], v160 offset:2048
	ds_read_b128 v[160:163], v160 offset:3072
	ds_read_b128 v[174:177], v186
	ds_read_b128 v[190:193], v186 offset:1024
	ds_read_b128 v[194:197], v186 offset:2048
	ds_read_b128 v[198:201], v186 offset:3072
	ds_read_b128 v[202:205], v186 offset:4096
	ds_read_b128 v[214:217], v186 offset:5120
	ds_read_b128 v[218:221], v186 offset:6144
	ds_read_b128 v[222:225], v186 offset:7168
	s_waitcnt vmcnt(8)
	s_waitcnt lgkmcnt(0)
	s_barrier
	s_setprio 1
	s_waitcnt lgkmcnt(0)
	v_mfma_f32_16x16x32_bf16 v[128:131], v[132:135], v[174:177], v[128:131]
	v_mfma_f32_16x16x32_bf16 v[124:127], v[140:143], v[174:177], v[124:127]
	v_mfma_f32_16x16x32_bf16 v[108:111], v[132:135], v[194:197], v[108:111]
	v_mfma_f32_16x16x32_bf16 v[116:119], v[140:143], v[194:197], v[116:119]
	v_mfma_f32_16x16x32_bf16 v[92:95], v[132:135], v[202:205], v[92:95]
	v_mfma_f32_16x16x32_bf16 v[88:91], v[140:143], v[202:205], v[88:91]
	v_mfma_f32_16x16x32_bf16 v[76:79], v[132:135], v[218:221], v[76:79]
	v_mfma_f32_16x16x32_bf16 v[80:83], v[140:143], v[218:221], v[80:83]
	v_mfma_f32_16x16x32_bf16 v[128:131], v[136:139], v[190:193], v[128:131]
	v_mfma_f32_16x16x32_bf16 v[124:127], v[144:147], v[190:193], v[124:127]
	v_mfma_f32_16x16x32_bf16 v[108:111], v[136:139], v[198:201], v[108:111]
	v_mfma_f32_16x16x32_bf16 v[116:119], v[144:147], v[198:201], v[116:119]
	v_mfma_f32_16x16x32_bf16 v[92:95], v[136:139], v[214:217], v[92:95]
	v_mfma_f32_16x16x32_bf16 v[88:91], v[144:147], v[214:217], v[88:91]
	v_mfma_f32_16x16x32_bf16 v[76:79], v[136:139], v[222:225], v[76:79]
	v_mfma_f32_16x16x32_bf16 v[80:83], v[144:147], v[222:225], v[80:83]
	s_setprio 0
	s_setprio 1
	v_mfma_f32_16x16x32_bf16 v[120:123], v[148:151], v[174:177], v[120:123]
	v_mfma_f32_16x16x32_bf16 v[104:107], v[156:159], v[174:177], v[104:107]
	v_mfma_f32_16x16x32_bf16 v[100:103], v[148:151], v[194:197], v[100:103]
	v_mfma_f32_16x16x32_bf16 v[96:99], v[156:159], v[194:197], v[96:99]
	v_mfma_f32_16x16x32_bf16 v[84:87], v[148:151], v[202:205], v[84:87]
	v_mfma_f32_16x16x32_bf16 v[72:75], v[156:159], v[202:205], v[72:75]
	v_mfma_f32_16x16x32_bf16 v[68:71], v[148:151], v[218:221], v[68:71]
	v_mfma_f32_16x16x32_bf16 v[64:67], v[156:159], v[218:221], v[64:67]
	v_mfma_f32_16x16x32_bf16 v[120:123], v[152:155], v[190:193], v[120:123]
	v_mfma_f32_16x16x32_bf16 v[104:107], v[160:163], v[190:193], v[104:107]
	v_mfma_f32_16x16x32_bf16 v[100:103], v[152:155], v[198:201], v[100:103]
	v_mfma_f32_16x16x32_bf16 v[96:99], v[160:163], v[198:201], v[96:99]
	v_mfma_f32_16x16x32_bf16 v[84:87], v[152:155], v[214:217], v[84:87]
	v_mfma_f32_16x16x32_bf16 v[72:75], v[160:163], v[214:217], v[72:75]
	v_mfma_f32_16x16x32_bf16 v[68:71], v[152:155], v[222:225], v[68:71]
	v_mfma_f32_16x16x32_bf16 v[64:67], v[160:163], v[222:225], v[64:67]
	s_setprio 0
	s_barrier
	s_add_i32 s55, s55, s38
	v_lshl_add_u64 v[206:207], s[22:23], 0, v[164:165]
	s_mov_b32 m0, s55
	s_nop 0
	global_load_lds_dwordx4 v[206:207], off
	s_add_i32 m0, s55, 0x2000
	s_add_u32 s60, s22, 0x4000
	v_lshl_add_u64 v[206:207], s[22:23], 0, v[168:169]
	s_addc_u32 s61, s23, 0
	s_add_i32 s55, s63, s38
	global_load_lds_dwordx4 v[206:207], off
	v_lshl_add_u64 v[206:207], s[60:61], 0, v[164:165]
	s_mov_b32 m0, s55
	v_lshl_add_u64 v[208:209], s[24:25], 0, v[166:167]
	global_load_lds_dwordx4 v[206:207], off
	v_lshl_add_u64 v[206:207], s[60:61], 0, v[168:169]
	s_add_i32 m0, s55, 0x2000
	s_nop 0
	global_load_lds_dwordx4 v[206:207], off
	v_lshl_add_u64 v[206:207], s[24:25], 0, v[2:3]
	s_mov_b32 m0, s39
	s_nop 0
	global_load_lds_dwordx4 v[206:207], off
	s_mov_b32 m0, s44
	s_nop 0
	global_load_lds_dwordx4 v[208:209], off
	ds_read_b128 v[174:177], v186 offset:16384
	ds_read_b128 v[190:193], v186 offset:17408
	ds_read_b128 v[194:197], v186 offset:18432
	ds_read_b128 v[198:201], v186 offset:19456
	ds_read_b128 v[202:205], v186 offset:20480
	ds_read_b128 v[214:217], v186 offset:21504
	ds_read_b128 v[218:221], v186 offset:22528
	ds_read_b128 v[222:225], v186 offset:23552
	s_waitcnt vmcnt(8)
	s_waitcnt lgkmcnt(0)
	s_barrier
	s_setprio 1
	s_waitcnt lgkmcnt(0)
	v_mfma_f32_16x16x32_bf16 v[60:63], v[132:135], v[174:177], v[60:63]
	v_mfma_f32_16x16x32_bf16 v[56:59], v[140:143], v[174:177], v[56:59]
	v_mfma_f32_16x16x32_bf16 v[44:47], v[132:135], v[194:197], v[44:47]
	v_mfma_f32_16x16x32_bf16 v[48:51], v[140:143], v[194:197], v[48:51]
	v_mfma_f32_16x16x32_bf16 v[28:31], v[132:135], v[202:205], v[28:31]
	v_mfma_f32_16x16x32_bf16 v[24:27], v[140:143], v[202:205], v[24:27]
	v_mfma_f32_16x16x32_bf16 v[112:115], v[132:135], v[218:221], v[112:115]
	v_mfma_f32_16x16x32_bf16 v[16:19], v[140:143], v[218:221], v[16:19]
	v_mfma_f32_16x16x32_bf16 v[60:63], v[136:139], v[190:193], v[60:63]
	v_mfma_f32_16x16x32_bf16 v[56:59], v[144:147], v[190:193], v[56:59]
	v_mfma_f32_16x16x32_bf16 v[44:47], v[136:139], v[198:201], v[44:47]
	v_mfma_f32_16x16x32_bf16 v[48:51], v[144:147], v[198:201], v[48:51]
	v_mfma_f32_16x16x32_bf16 v[28:31], v[136:139], v[214:217], v[28:31]
	v_mfma_f32_16x16x32_bf16 v[24:27], v[144:147], v[214:217], v[24:27]
	v_mfma_f32_16x16x32_bf16 v[112:115], v[136:139], v[222:225], v[112:115]
	v_mfma_f32_16x16x32_bf16 v[16:19], v[144:147], v[222:225], v[16:19]
	s_setprio 0
	s_setprio 1
	v_mfma_f32_16x16x32_bf16 v[52:55], v[148:151], v[174:177], v[52:55]
	v_mfma_f32_16x16x32_bf16 v[40:43], v[156:159], v[174:177], v[40:43]
	v_mfma_f32_16x16x32_bf16 v[36:39], v[148:151], v[194:197], v[36:39]
	v_mfma_f32_16x16x32_bf16 v[32:35], v[156:159], v[194:197], v[32:35]
	v_mfma_f32_16x16x32_bf16 v[20:23], v[148:151], v[202:205], v[20:23]
	v_mfma_f32_16x16x32_bf16 v[12:15], v[156:159], v[202:205], v[12:15]
	v_mfma_f32_16x16x32_bf16 v[4:7], v[148:151], v[218:221], v[4:7]
	v_mfma_f32_16x16x32_bf16 v[8:11], v[156:159], v[218:221], v[8:11]
	v_mfma_f32_16x16x32_bf16 v[52:55], v[152:155], v[190:193], v[52:55]
	v_mfma_f32_16x16x32_bf16 v[40:43], v[160:163], v[190:193], v[40:43]
	v_mfma_f32_16x16x32_bf16 v[36:39], v[152:155], v[198:201], v[36:39]
	v_mfma_f32_16x16x32_bf16 v[32:35], v[160:163], v[198:201], v[32:35]
	v_mfma_f32_16x16x32_bf16 v[20:23], v[152:155], v[214:217], v[20:23]
	v_mfma_f32_16x16x32_bf16 v[12:15], v[160:163], v[214:217], v[12:15]
	v_mfma_f32_16x16x32_bf16 v[4:7], v[152:155], v[222:225], v[4:7]
	v_mfma_f32_16x16x32_bf16 v[8:11], v[160:163], v[222:225], v[8:11]
	s_setprio 0
	s_barrier
	s_add_i32 s55, 0, 0x18000
	s_add_i32 s60, 0, 0x1c000
	s_add_u32 s24, s24, 0x80000
	s_addc_u32 s25, s25, 0
	s_mov_b32 m0, s45
	v_lshl_add_u64 v[210:211], s[24:25], 0, v[2:3]
	global_load_lds_dwordx4 v[210:211], off
	v_lshl_add_u64 v[210:211], s[24:25], 0, v[166:167]
	s_mov_b32 m0, s50
	s_nop 0
	global_load_lds_dwordx4 v[210:211], off
	v_add_u32_e32 v144, s55, v178
	v_add_u32_e32 v160, s60, v178
	ds_read_b128 v[132:135], v144
	ds_read_b128 v[136:139], v144 offset:1024
	ds_read_b128 v[140:143], v144 offset:2048
	ds_read_b128 v[144:147], v144 offset:3072
	ds_read_b128 v[148:151], v160
	ds_read_b128 v[152:155], v160 offset:1024
	ds_read_b128 v[156:159], v160 offset:2048
	ds_read_b128 v[160:163], v160 offset:3072
	ds_read_b128 v[174:177], v186 offset:32768
	ds_read_b128 v[190:193], v186 offset:33792
	ds_read_b128 v[194:197], v186 offset:34816
	ds_read_b128 v[198:201], v186 offset:35840
	ds_read_b128 v[202:205], v186 offset:36864
	ds_read_b128 v[214:217], v186 offset:37888
	ds_read_b128 v[218:221], v186 offset:38912
	ds_read_b128 v[222:225], v186 offset:39936
	s_waitcnt vmcnt(8)
	s_waitcnt lgkmcnt(0)
	s_barrier
	s_setprio 1
	s_waitcnt lgkmcnt(0)
	v_mfma_f32_16x16x32_bf16 v[128:131], v[132:135], v[174:177], v[128:131]
	v_mfma_f32_16x16x32_bf16 v[124:127], v[140:143], v[174:177], v[124:127]
	v_mfma_f32_16x16x32_bf16 v[108:111], v[132:135], v[194:197], v[108:111]
	v_mfma_f32_16x16x32_bf16 v[116:119], v[140:143], v[194:197], v[116:119]
	v_mfma_f32_16x16x32_bf16 v[92:95], v[132:135], v[202:205], v[92:95]
	v_mfma_f32_16x16x32_bf16 v[88:91], v[140:143], v[202:205], v[88:91]
	v_mfma_f32_16x16x32_bf16 v[76:79], v[132:135], v[218:221], v[76:79]
	v_mfma_f32_16x16x32_bf16 v[80:83], v[140:143], v[218:221], v[80:83]
	v_mfma_f32_16x16x32_bf16 v[128:131], v[136:139], v[190:193], v[128:131]
	v_mfma_f32_16x16x32_bf16 v[124:127], v[144:147], v[190:193], v[124:127]
	v_mfma_f32_16x16x32_bf16 v[108:111], v[136:139], v[198:201], v[108:111]
	v_mfma_f32_16x16x32_bf16 v[116:119], v[144:147], v[198:201], v[116:119]
	v_mfma_f32_16x16x32_bf16 v[92:95], v[136:139], v[214:217], v[92:95]
	v_mfma_f32_16x16x32_bf16 v[88:91], v[144:147], v[214:217], v[88:91]
	v_mfma_f32_16x16x32_bf16 v[76:79], v[136:139], v[222:225], v[76:79]
	v_mfma_f32_16x16x32_bf16 v[80:83], v[144:147], v[222:225], v[80:83]
	s_setprio 0
	s_setprio 1
	v_mfma_f32_16x16x32_bf16 v[120:123], v[148:151], v[174:177], v[120:123]
	v_mfma_f32_16x16x32_bf16 v[104:107], v[156:159], v[174:177], v[104:107]
	v_mfma_f32_16x16x32_bf16 v[100:103], v[148:151], v[194:197], v[100:103]
	v_mfma_f32_16x16x32_bf16 v[96:99], v[156:159], v[194:197], v[96:99]
	v_mfma_f32_16x16x32_bf16 v[84:87], v[148:151], v[202:205], v[84:87]
	v_mfma_f32_16x16x32_bf16 v[72:75], v[156:159], v[202:205], v[72:75]
	v_mfma_f32_16x16x32_bf16 v[68:71], v[148:151], v[218:221], v[68:71]
	v_mfma_f32_16x16x32_bf16 v[64:67], v[156:159], v[218:221], v[64:67]
	v_mfma_f32_16x16x32_bf16 v[120:123], v[152:155], v[190:193], v[120:123]
	v_mfma_f32_16x16x32_bf16 v[104:107], v[160:163], v[190:193], v[104:107]
	v_mfma_f32_16x16x32_bf16 v[100:103], v[152:155], v[198:201], v[100:103]
	v_mfma_f32_16x16x32_bf16 v[96:99], v[160:163], v[198:201], v[96:99]
	v_mfma_f32_16x16x32_bf16 v[84:87], v[152:155], v[214:217], v[84:87]
	v_mfma_f32_16x16x32_bf16 v[72:75], v[160:163], v[214:217], v[72:75]
	v_mfma_f32_16x16x32_bf16 v[68:71], v[152:155], v[222:225], v[68:71]
	v_mfma_f32_16x16x32_bf16 v[64:67], v[160:163], v[222:225], v[64:67]
	s_setprio 0
	s_barrier
	s_add_u32 s24, s22, 0x8000
	s_addc_u32 s25, s23, 0
	s_add_i32 s55, s55, s38
	v_lshl_add_u64 v[210:211], s[24:25], 0, v[164:165]
	s_mov_b32 m0, s55
	s_nop 0
	global_load_lds_dwordx4 v[210:211], off
	s_add_i32 m0, s55, 0x2000
	s_add_u32 s22, s22, 0xc000
	v_lshl_add_u64 v[210:211], s[24:25], 0, v[168:169]
	s_addc_u32 s23, s23, 0
	s_add_i32 s24, s60, s38
	global_load_lds_dwordx4 v[210:211], off
	v_lshl_add_u64 v[210:211], s[22:23], 0, v[164:165]
	s_mov_b32 m0, s24
	v_lshl_add_u64 v[206:207], v[206:207], 0, s[74:75]
	global_load_lds_dwordx4 v[210:211], off
	v_lshl_add_u64 v[210:211], s[22:23], 0, v[168:169]
	s_add_i32 m0, s24, 0x2000
	s_nop 0
	global_load_lds_dwordx4 v[210:211], off
	s_mov_b32 m0, s56
	s_nop 0
	global_load_lds_dwordx4 v[206:207], off
	v_lshl_add_u64 v[206:207], v[208:209], 0, s[74:75]
	s_mov_b32 m0, s57
	s_nop 0
	global_load_lds_dwordx4 v[206:207], off
	ds_read_b128 v[174:177], v186 offset:49152
	ds_read_b128 v[190:193], v186 offset:50176
	ds_read_b128 v[194:197], v186 offset:51200
	ds_read_b128 v[198:201], v186 offset:52224
	ds_read_b128 v[202:205], v186 offset:53248
	ds_read_b128 v[214:217], v186 offset:54272
	ds_read_b128 v[218:221], v186 offset:55296
	ds_read_b128 v[222:225], v186 offset:56320
	s_waitcnt vmcnt(8)
	s_waitcnt lgkmcnt(0)
	s_barrier
	s_setprio 1
	s_waitcnt lgkmcnt(0)
	v_mfma_f32_16x16x32_bf16 v[60:63], v[132:135], v[174:177], v[60:63]
	v_mfma_f32_16x16x32_bf16 v[56:59], v[140:143], v[174:177], v[56:59]
	v_mfma_f32_16x16x32_bf16 v[44:47], v[132:135], v[194:197], v[44:47]
	v_mfma_f32_16x16x32_bf16 v[48:51], v[140:143], v[194:197], v[48:51]
	v_mfma_f32_16x16x32_bf16 v[28:31], v[132:135], v[202:205], v[28:31]
	v_mfma_f32_16x16x32_bf16 v[24:27], v[140:143], v[202:205], v[24:27]
	v_mfma_f32_16x16x32_bf16 v[112:115], v[132:135], v[218:221], v[112:115]
	v_mfma_f32_16x16x32_bf16 v[16:19], v[140:143], v[218:221], v[16:19]
	v_mfma_f32_16x16x32_bf16 v[60:63], v[136:139], v[190:193], v[60:63]
	v_mfma_f32_16x16x32_bf16 v[56:59], v[144:147], v[190:193], v[56:59]
	v_mfma_f32_16x16x32_bf16 v[44:47], v[136:139], v[198:201], v[44:47]
	v_mfma_f32_16x16x32_bf16 v[48:51], v[144:147], v[198:201], v[48:51]
	v_mfma_f32_16x16x32_bf16 v[28:31], v[136:139], v[214:217], v[28:31]
	v_mfma_f32_16x16x32_bf16 v[24:27], v[144:147], v[214:217], v[24:27]
	v_mfma_f32_16x16x32_bf16 v[112:115], v[136:139], v[222:225], v[112:115]
	v_mfma_f32_16x16x32_bf16 v[16:19], v[144:147], v[222:225], v[16:19]
	s_setprio 0
	s_setprio 1
	v_mfma_f32_16x16x32_bf16 v[52:55], v[148:151], v[174:177], v[52:55]
	v_mfma_f32_16x16x32_bf16 v[40:43], v[156:159], v[174:177], v[40:43]
	v_mfma_f32_16x16x32_bf16 v[36:39], v[148:151], v[194:197], v[36:39]
	v_mfma_f32_16x16x32_bf16 v[32:35], v[156:159], v[194:197], v[32:35]
	v_mfma_f32_16x16x32_bf16 v[20:23], v[148:151], v[202:205], v[20:23]
	v_mfma_f32_16x16x32_bf16 v[12:15], v[156:159], v[202:205], v[12:15]
	v_mfma_f32_16x16x32_bf16 v[4:7], v[148:151], v[218:221], v[4:7]
	v_mfma_f32_16x16x32_bf16 v[8:11], v[156:159], v[218:221], v[8:11]
	v_mfma_f32_16x16x32_bf16 v[52:55], v[152:155], v[190:193], v[52:55]
	v_mfma_f32_16x16x32_bf16 v[40:43], v[160:163], v[190:193], v[40:43]
	v_mfma_f32_16x16x32_bf16 v[36:39], v[152:155], v[198:201], v[36:39]
	v_mfma_f32_16x16x32_bf16 v[32:35], v[160:163], v[198:201], v[32:35]
	v_mfma_f32_16x16x32_bf16 v[20:23], v[152:155], v[214:217], v[20:23]
	v_mfma_f32_16x16x32_bf16 v[12:15], v[160:163], v[214:217], v[12:15]
	v_mfma_f32_16x16x32_bf16 v[4:7], v[152:155], v[222:225], v[4:7]
	v_mfma_f32_16x16x32_bf16 v[8:11], v[160:163], v[222:225], v[8:11]
	s_setprio 0
	s_barrier
	s_add_i32 s54, s54, 2
	s_add_u32 s29, s29, 0x10000
	s_addc_u32 s49, s49, 0
	s_add_u32 s20, s20, 0x100
	s_addc_u32 s21, s21, 0
	s_cmp_gt_u32 s54, 29
	s_cbranch_scc0 .LBB0_640
	v_readlane_b32 s20, v254, 52
	v_readlane_b32 s21, v254, 53
	s_and_b64 vcc, exec, s[20:21]
	s_cbranch_vccz .LBB0_643
	s_barrier

.LBB0_744:
	s_add_u32 s18, s16, 0xfff80080
	s_addc_u32 s19, s17, -1
	s_add_i32 s50, 0, 0x10000
	s_cmp_eq_u32 s49, 28
	s_cselect_b32 s21, s7, s19
	s_cselect_b32 s20, s45, s18
	s_cselect_b32 s19, s11, s48
	s_cselect_b32 s18, s46, s47
	s_add_i32 s52, 0, 0x14000
	v_lshl_add_u64 v[208:209], s[16:17], 0, v[150:151]
	s_add_i32 m0, s30, 0xc000
	s_nop 0
	global_load_lds_dwordx4 v[208:209], off
	v_lshl_add_u64 v[208:209], s[16:17], 0, v[152:153]
	s_add_i32 m0, s30, 0xe000
	s_nop 0
	global_load_lds_dwordx4 v[208:209], off
	v_add_u32_e32 v168, s50, v158
	v_add_u32_e32 v184, s52, v158
	ds_read_b128 v[154:157], v168
	ds_read_b128 v[160:163], v168 offset:1024
	ds_read_b128 v[164:167], v168 offset:2048
	ds_read_b128 v[168:171], v168 offset:3072
	ds_read_b128 v[172:175], v184
	ds_read_b128 v[176:179], v184 offset:1024
	ds_read_b128 v[180:183], v184 offset:2048
	ds_read_b128 v[184:187], v184 offset:3072
	ds_read_b128 v[188:191], v159
	ds_read_b128 v[192:195], v159 offset:1024
	ds_read_b128 v[196:199], v159 offset:2048
	ds_read_b128 v[200:203], v159 offset:3072
	ds_read_b128 v[204:207], v159 offset:4096
	ds_read_b128 v[214:217], v159 offset:5120
	ds_read_b128 v[218:221], v159 offset:6144
	ds_read_b128 v[222:225], v159 offset:7168
	s_waitcnt vmcnt(8)
	s_waitcnt lgkmcnt(0)
	s_barrier
	s_setprio 1
	s_waitcnt lgkmcnt(0)
	v_mfma_f32_16x16x32_bf16 v[128:131], v[154:157], v[188:191], v[128:131]
	v_mfma_f32_16x16x32_bf16 v[120:123], v[164:167], v[188:191], v[120:123]
	v_mfma_f32_16x16x32_bf16 v[112:115], v[154:157], v[196:199], v[112:115]
	v_mfma_f32_16x16x32_bf16 v[104:107], v[164:167], v[196:199], v[104:107]
	v_mfma_f32_16x16x32_bf16 v[96:99], v[154:157], v[204:207], v[96:99]
	v_mfma_f32_16x16x32_bf16 v[88:91], v[164:167], v[204:207], v[88:91]
	v_mfma_f32_16x16x32_bf16 v[80:83], v[154:157], v[218:221], v[80:83]
	v_mfma_f32_16x16x32_bf16 v[72:75], v[164:167], v[218:221], v[72:75]
	v_mfma_f32_16x16x32_bf16 v[128:131], v[160:163], v[192:195], v[128:131]
	v_mfma_f32_16x16x32_bf16 v[120:123], v[168:171], v[192:195], v[120:123]
	v_mfma_f32_16x16x32_bf16 v[112:115], v[160:163], v[200:203], v[112:115]
	v_mfma_f32_16x16x32_bf16 v[104:107], v[168:171], v[200:203], v[104:107]
	v_mfma_f32_16x16x32_bf16 v[96:99], v[160:163], v[214:217], v[96:99]
	v_mfma_f32_16x16x32_bf16 v[88:91], v[168:171], v[214:217], v[88:91]
	v_mfma_f32_16x16x32_bf16 v[80:83], v[160:163], v[222:225], v[80:83]
	v_mfma_f32_16x16x32_bf16 v[72:75], v[168:171], v[222:225], v[72:75]
	s_setprio 0
	s_setprio 1
	v_mfma_f32_16x16x32_bf16 v[124:127], v[172:175], v[188:191], v[124:127]
	v_mfma_f32_16x16x32_bf16 v[116:119], v[180:183], v[188:191], v[116:119]
	v_mfma_f32_16x16x32_bf16 v[108:111], v[172:175], v[196:199], v[108:111]
	v_mfma_f32_16x16x32_bf16 v[100:103], v[180:183], v[196:199], v[100:103]
	v_mfma_f32_16x16x32_bf16 v[92:95], v[172:175], v[204:207], v[92:95]
	v_mfma_f32_16x16x32_bf16 v[84:87], v[180:183], v[204:207], v[84:87]
	v_mfma_f32_16x16x32_bf16 v[76:79], v[172:175], v[218:221], v[76:79]
	v_mfma_f32_16x16x32_bf16 v[68:71], v[180:183], v[218:221], v[68:71]
	v_mfma_f32_16x16x32_bf16 v[124:127], v[176:179], v[192:195], v[124:127]
	v_mfma_f32_16x16x32_bf16 v[116:119], v[184:187], v[192:195], v[116:119]
	v_mfma_f32_16x16x32_bf16 v[108:111], v[176:179], v[200:203], v[108:111]
	v_mfma_f32_16x16x32_bf16 v[100:103], v[184:187], v[200:203], v[100:103]
	v_mfma_f32_16x16x32_bf16 v[92:95], v[176:179], v[214:217], v[92:95]
	v_mfma_f32_16x16x32_bf16 v[84:87], v[184:187], v[214:217], v[84:87]
	v_mfma_f32_16x16x32_bf16 v[76:79], v[176:179], v[222:225], v[76:79]
	v_mfma_f32_16x16x32_bf16 v[68:71], v[184:187], v[222:225], v[68:71]
	s_setprio 0
	s_barrier
	s_add_i32 s50, s50, s29
	v_lshl_add_u64 v[208:209], s[18:19], 0, v[136:137]
	s_mov_b32 m0, s50
	s_nop 0
	global_load_lds_dwordx4 v[208:209], off
	s_add_i32 m0, s50, 0x2000
	s_add_u32 s50, s18, 0x4000
	v_lshl_add_u64 v[208:209], s[18:19], 0, v[132:133]
	s_addc_u32 s51, s19, 0
	s_add_i32 s52, s52, s29
	global_load_lds_dwordx4 v[208:209], off
	v_lshl_add_u64 v[208:209], s[50:51], 0, v[136:137]
	s_mov_b32 m0, s52
	v_lshl_add_u64 v[210:211], s[20:21], 0, v[134:135]
	global_load_lds_dwordx4 v[208:209], off
	v_lshl_add_u64 v[208:209], s[50:51], 0, v[132:133]
	s_add_i32 m0, s52, 0x2000
	s_nop 0
	global_load_lds_dwordx4 v[208:209], off
	v_lshl_add_u64 v[208:209], s[20:21], 0, v[138:139]
	s_mov_b32 m0, s30
	s_nop 0
	global_load_lds_dwordx4 v[208:209], off
	s_mov_b32 m0, s31
	s_nop 0
	global_load_lds_dwordx4 v[210:211], off
	ds_read_b128 v[188:191], v159 offset:16384
	ds_read_b128 v[192:195], v159 offset:17408
	ds_read_b128 v[196:199], v159 offset:18432
	ds_read_b128 v[200:203], v159 offset:19456
	ds_read_b128 v[204:207], v159 offset:20480
	ds_read_b128 v[214:217], v159 offset:21504
	ds_read_b128 v[218:221], v159 offset:22528
	ds_read_b128 v[222:225], v159 offset:23552
	s_waitcnt vmcnt(8)
	s_waitcnt lgkmcnt(0)
	s_barrier
	s_setprio 1
	s_waitcnt lgkmcnt(0)
	v_mfma_f32_16x16x32_bf16 v[64:67], v[154:157], v[188:191], v[64:67]
	v_mfma_f32_16x16x32_bf16 v[56:59], v[164:167], v[188:191], v[56:59]
	v_mfma_f32_16x16x32_bf16 v[48:51], v[154:157], v[196:199], v[48:51]
	v_mfma_f32_16x16x32_bf16 v[40:43], v[164:167], v[196:199], v[40:43]
	v_mfma_f32_16x16x32_bf16 v[32:35], v[154:157], v[204:207], v[32:35]
	v_mfma_f32_16x16x32_bf16 v[24:27], v[164:167], v[204:207], v[24:27]
	v_mfma_f32_16x16x32_bf16 v[16:19], v[154:157], v[218:221], v[16:19]
	v_mfma_f32_16x16x32_bf16 v[8:11], v[164:167], v[218:221], v[8:11]
	v_mfma_f32_16x16x32_bf16 v[64:67], v[160:163], v[192:195], v[64:67]
	v_mfma_f32_16x16x32_bf16 v[56:59], v[168:171], v[192:195], v[56:59]
	v_mfma_f32_16x16x32_bf16 v[48:51], v[160:163], v[200:203], v[48:51]
	v_mfma_f32_16x16x32_bf16 v[40:43], v[168:171], v[200:203], v[40:43]
	v_mfma_f32_16x16x32_bf16 v[32:35], v[160:163], v[214:217], v[32:35]
	v_mfma_f32_16x16x32_bf16 v[24:27], v[168:171], v[214:217], v[24:27]
	v_mfma_f32_16x16x32_bf16 v[16:19], v[160:163], v[222:225], v[16:19]
	v_mfma_f32_16x16x32_bf16 v[8:11], v[168:171], v[222:225], v[8:11]
	s_setprio 0
	s_setprio 1
	v_mfma_f32_16x16x32_bf16 v[60:63], v[172:175], v[188:191], v[60:63]
	v_mfma_f32_16x16x32_bf16 v[52:55], v[180:183], v[188:191], v[52:55]
	v_mfma_f32_16x16x32_bf16 v[44:47], v[172:175], v[196:199], v[44:47]
	v_mfma_f32_16x16x32_bf16 v[36:39], v[180:183], v[196:199], v[36:39]
	v_mfma_f32_16x16x32_bf16 v[28:31], v[172:175], v[204:207], v[28:31]
	v_mfma_f32_16x16x32_bf16 v[20:23], v[180:183], v[204:207], v[20:23]
	v_mfma_f32_16x16x32_bf16 v[12:15], v[172:175], v[218:221], v[12:15]
	v_mfma_f32_16x16x32_bf16 v[4:7], v[180:183], v[218:221], v[4:7]
	v_mfma_f32_16x16x32_bf16 v[60:63], v[176:179], v[192:195], v[60:63]
	v_mfma_f32_16x16x32_bf16 v[52:55], v[184:187], v[192:195], v[52:55]
	v_mfma_f32_16x16x32_bf16 v[44:47], v[176:179], v[200:203], v[44:47]
	v_mfma_f32_16x16x32_bf16 v[36:39], v[184:187], v[200:203], v[36:39]
	v_mfma_f32_16x16x32_bf16 v[28:31], v[176:179], v[214:217], v[28:31]
	v_mfma_f32_16x16x32_bf16 v[20:23], v[184:187], v[214:217], v[20:23]
	v_mfma_f32_16x16x32_bf16 v[12:15], v[176:179], v[222:225], v[12:15]
	v_mfma_f32_16x16x32_bf16 v[4:7], v[184:187], v[222:225], v[4:7]
	s_setprio 0
	s_barrier
	s_add_i32 s50, 0, 0x18000
	s_add_i32 s51, 0, 0x1c000
	s_add_u32 s20, s20, 0x80000
	s_addc_u32 s21, s21, 0
	s_mov_b32 m0, s34
	v_lshl_add_u64 v[226:227], s[20:21], 0, v[138:139]
	global_load_lds_dwordx4 v[226:227], off
	v_lshl_add_u64 v[226:227], s[20:21], 0, v[134:135]
	s_mov_b32 m0, s35
	s_nop 0
	global_load_lds_dwordx4 v[226:227], off
	v_add_u32_e32 v168, s50, v158
	v_add_u32_e32 v184, s51, v158
	ds_read_b128 v[154:157], v168
	ds_read_b128 v[160:163], v168 offset:1024
	ds_read_b128 v[164:167], v168 offset:2048
	ds_read_b128 v[168:171], v168 offset:3072
	ds_read_b128 v[172:175], v184
	ds_read_b128 v[176:179], v184 offset:1024
	ds_read_b128 v[180:183], v184 offset:2048
	ds_read_b128 v[184:187], v184 offset:3072
	ds_read_b128 v[188:191], v159 offset:32768
	ds_read_b128 v[192:195], v159 offset:33792
	ds_read_b128 v[196:199], v159 offset:34816
	ds_read_b128 v[200:203], v159 offset:35840
	ds_read_b128 v[204:207], v159 offset:36864
	ds_read_b128 v[214:217], v159 offset:37888
	ds_read_b128 v[218:221], v159 offset:38912
	ds_read_b128 v[222:225], v159 offset:39936
	s_waitcnt vmcnt(8)
	s_waitcnt lgkmcnt(0)
	s_barrier
	s_setprio 1
	s_waitcnt lgkmcnt(0)
	v_mfma_f32_16x16x32_bf16 v[128:131], v[154:157], v[188:191], v[128:131]
	v_mfma_f32_16x16x32_bf16 v[120:123], v[164:167], v[188:191], v[120:123]
	v_mfma_f32_16x16x32_bf16 v[112:115], v[154:157], v[196:199], v[112:115]
	v_mfma_f32_16x16x32_bf16 v[104:107], v[164:167], v[196:199], v[104:107]
	v_mfma_f32_16x16x32_bf16 v[96:99], v[154:157], v[204:207], v[96:99]
	v_mfma_f32_16x16x32_bf16 v[88:91], v[164:167], v[204:207], v[88:91]
	v_mfma_f32_16x16x32_bf16 v[80:83], v[154:157], v[218:221], v[80:83]
	v_mfma_f32_16x16x32_bf16 v[72:75], v[164:167], v[218:221], v[72:75]
	v_mfma_f32_16x16x32_bf16 v[128:131], v[160:163], v[192:195], v[128:131]
	v_mfma_f32_16x16x32_bf16 v[120:123], v[168:171], v[192:195], v[120:123]
	v_mfma_f32_16x16x32_bf16 v[112:115], v[160:163], v[200:203], v[112:115]
	v_mfma_f32_16x16x32_bf16 v[104:107], v[168:171], v[200:203], v[104:107]
	v_mfma_f32_16x16x32_bf16 v[96:99], v[160:163], v[214:217], v[96:99]
	v_mfma_f32_16x16x32_bf16 v[88:91], v[168:171], v[214:217], v[88:91]
	v_mfma_f32_16x16x32_bf16 v[80:83], v[160:163], v[222:225], v[80:83]
	v_mfma_f32_16x16x32_bf16 v[72:75], v[168:171], v[222:225], v[72:75]
	s_setprio 0
	s_setprio 1
	v_mfma_f32_16x16x32_bf16 v[124:127], v[172:175], v[188:191], v[124:127]
	v_mfma_f32_16x16x32_bf16 v[116:119], v[180:183], v[188:191], v[116:119]
	v_mfma_f32_16x16x32_bf16 v[108:111], v[172:175], v[196:199], v[108:111]
	v_mfma_f32_16x16x32_bf16 v[100:103], v[180:183], v[196:199], v[100:103]
	v_mfma_f32_16x16x32_bf16 v[92:95], v[172:175], v[204:207], v[92:95]
	v_mfma_f32_16x16x32_bf16 v[84:87], v[180:183], v[204:207], v[84:87]
	v_mfma_f32_16x16x32_bf16 v[76:79], v[172:175], v[218:221], v[76:79]
	v_mfma_f32_16x16x32_bf16 v[68:71], v[180:183], v[218:221], v[68:71]
	v_mfma_f32_16x16x32_bf16 v[124:127], v[176:179], v[192:195], v[124:127]
	v_mfma_f32_16x16x32_bf16 v[116:119], v[184:187], v[192:195], v[116:119]
	v_mfma_f32_16x16x32_bf16 v[108:111], v[176:179], v[200:203], v[108:111]
	v_mfma_f32_16x16x32_bf16 v[100:103], v[184:187], v[200:203], v[100:103]
	v_mfma_f32_16x16x32_bf16 v[92:95], v[176:179], v[214:217], v[92:95]
	v_mfma_f32_16x16x32_bf16 v[84:87], v[184:187], v[214:217], v[84:87]
	v_mfma_f32_16x16x32_bf16 v[76:79], v[176:179], v[222:225], v[76:79]
	v_mfma_f32_16x16x32_bf16 v[68:71], v[184:187], v[222:225], v[68:71]
	s_setprio 0
	s_barrier
	s_add_u32 s20, s18, 0x8000
	s_addc_u32 s21, s19, 0
	s_add_i32 s50, s50, s29
	v_lshl_add_u64 v[226:227], s[20:21], 0, v[136:137]
	s_mov_b32 m0, s50
	s_nop 0
	global_load_lds_dwordx4 v[226:227], off
	s_add_i32 m0, s50, 0x2000
	s_add_u32 s18, s18, 0xc000
	v_lshl_add_u64 v[226:227], s[20:21], 0, v[132:133]
	s_addc_u32 s19, s19, 0
	s_add_i32 s20, s51, s29
	global_load_lds_dwordx4 v[226:227], off
	v_lshl_add_u64 v[226:227], s[18:19], 0, v[136:137]
	s_mov_b32 m0, s20
	v_lshl_add_u64 v[208:209], v[208:209], 0, s[74:75]
	global_load_lds_dwordx4 v[226:227], off
	v_lshl_add_u64 v[226:227], s[18:19], 0, v[132:133]
	s_add_i32 m0, s20, 0x2000
	s_nop 0
	global_load_lds_dwordx4 v[226:227], off
	s_mov_b32 m0, s39
	s_nop 0
	global_load_lds_dwordx4 v[208:209], off
	v_lshl_add_u64 v[208:209], v[210:211], 0, s[74:75]
	s_mov_b32 m0, s40
	s_nop 0
	global_load_lds_dwordx4 v[208:209], off
	ds_read_b128 v[188:191], v159 offset:49152
	ds_read_b128 v[192:195], v159 offset:50176
	ds_read_b128 v[196:199], v159 offset:51200
	ds_read_b128 v[200:203], v159 offset:52224
	ds_read_b128 v[204:207], v159 offset:53248
	ds_read_b128 v[214:217], v159 offset:54272
	ds_read_b128 v[218:221], v159 offset:55296
	ds_read_b128 v[222:225], v159 offset:56320
	s_waitcnt vmcnt(8)
	s_waitcnt lgkmcnt(0)
	s_barrier
	s_setprio 1
	s_waitcnt lgkmcnt(0)
	v_mfma_f32_16x16x32_bf16 v[64:67], v[154:157], v[188:191], v[64:67]
	v_mfma_f32_16x16x32_bf16 v[56:59], v[164:167], v[188:191], v[56:59]
	v_mfma_f32_16x16x32_bf16 v[48:51], v[154:157], v[196:199], v[48:51]
	v_mfma_f32_16x16x32_bf16 v[40:43], v[164:167], v[196:199], v[40:43]
	v_mfma_f32_16x16x32_bf16 v[32:35], v[154:157], v[204:207], v[32:35]
	v_mfma_f32_16x16x32_bf16 v[24:27], v[164:167], v[204:207], v[24:27]
	v_mfma_f32_16x16x32_bf16 v[16:19], v[154:157], v[218:221], v[16:19]
	v_mfma_f32_16x16x32_bf16 v[8:11], v[164:167], v[218:221], v[8:11]
	v_mfma_f32_16x16x32_bf16 v[64:67], v[160:163], v[192:195], v[64:67]
	v_mfma_f32_16x16x32_bf16 v[56:59], v[168:171], v[192:195], v[56:59]
	v_mfma_f32_16x16x32_bf16 v[48:51], v[160:163], v[200:203], v[48:51]
	v_mfma_f32_16x16x32_bf16 v[40:43], v[168:171], v[200:203], v[40:43]
	v_mfma_f32_16x16x32_bf16 v[32:35], v[160:163], v[214:217], v[32:35]
	v_mfma_f32_16x16x32_bf16 v[24:27], v[168:171], v[214:217], v[24:27]
	v_mfma_f32_16x16x32_bf16 v[16:19], v[160:163], v[222:225], v[16:19]
	v_mfma_f32_16x16x32_bf16 v[8:11], v[168:171], v[222:225], v[8:11]
	s_setprio 0
	s_setprio 1
	v_mfma_f32_16x16x32_bf16 v[60:63], v[172:175], v[188:191], v[60:63]
	v_mfma_f32_16x16x32_bf16 v[52:55], v[180:183], v[188:191], v[52:55]
	v_mfma_f32_16x16x32_bf16 v[44:47], v[172:175], v[196:199], v[44:47]
	v_mfma_f32_16x16x32_bf16 v[36:39], v[180:183], v[196:199], v[36:39]
	v_mfma_f32_16x16x32_bf16 v[28:31], v[172:175], v[204:207], v[28:31]
	v_mfma_f32_16x16x32_bf16 v[20:23], v[180:183], v[204:207], v[20:23]
	v_mfma_f32_16x16x32_bf16 v[12:15], v[172:175], v[218:221], v[12:15]
	v_mfma_f32_16x16x32_bf16 v[4:7], v[180:183], v[218:221], v[4:7]
	v_mfma_f32_16x16x32_bf16 v[60:63], v[176:179], v[192:195], v[60:63]
	v_mfma_f32_16x16x32_bf16 v[52:55], v[184:187], v[192:195], v[52:55]
	v_mfma_f32_16x16x32_bf16 v[44:47], v[176:179], v[200:203], v[44:47]
	v_mfma_f32_16x16x32_bf16 v[36:39], v[184:187], v[200:203], v[36:39]
	v_mfma_f32_16x16x32_bf16 v[28:31], v[176:179], v[214:217], v[28:31]
	v_mfma_f32_16x16x32_bf16 v[20:23], v[184:187], v[214:217], v[20:23]
	v_mfma_f32_16x16x32_bf16 v[12:15], v[176:179], v[222:225], v[12:15]
	v_mfma_f32_16x16x32_bf16 v[4:7], v[184:187], v[222:225], v[4:7]
	s_setprio 0
	s_barrier
	s_add_i32 s49, s49, 2
	s_add_u32 s47, s47, 0x10000
	s_addc_u32 s48, s48, 0
	s_add_u32 s16, s16, 0x100
	s_addc_u32 s17, s17, 0
	s_cmp_gt_u32 s49, 29
	s_cbranch_scc0 .LBB0_744
	s_and_b64 vcc, exec, s[2:3]
	s_cbranch_vccz .LBB0_747
	s_barrier

.LBB0_810:
	s_add_u32 s20, s18, 0x4000
	s_addc_u32 s21, s19, 0
	s_cmpk_eq_i32 s26, 0x54
	s_cselect_b32 s24, s34, s20
	s_cselect_b32 s25, s35, s21
	s_cselect_b32 s22, s38, s6
	s_cselect_b32 s23, s39, s7
	s_add_u32 s20, s24, 0x8000
	s_addc_u32 s21, s25, 0
	s_add_i32 s27, 0, 0x10000
	s_add_i32 s45, 0, 0x14000
	v_lshl_add_u64 v[178:179], s[18:19], 0, v[162:163]
	s_add_i32 m0, s79, 0xc000
	s_nop 0
	global_load_lds_dwordx4 v[178:179], off
	v_lshl_add_u64 v[178:179], s[18:19], 0, v[164:165]
	s_add_i32 m0, s79, 0xe000
	s_nop 0
	global_load_lds_dwordx4 v[178:179], off
	v_add_u32_e32 v144, s27, v180
	v_add_u32_e32 v166, s45, v180
	ds_read_b128 v[132:135], v144
	ds_read_b128 v[136:139], v144 offset:1024
	ds_read_b128 v[140:143], v144 offset:2048
	ds_read_b128 v[144:147], v144 offset:3072
	ds_read_b128 v[148:151], v166
	ds_read_b128 v[152:155], v166 offset:1024
	ds_read_b128 v[156:159], v166 offset:2048
	ds_read_b128 v[166:169], v166 offset:3072
	ds_read_b128 v[170:173], v188
	ds_read_b128 v[174:177], v188 offset:1024
	ds_read_b128 v[192:195], v188 offset:2048
	ds_read_b128 v[196:199], v188 offset:3072
	ds_read_b128 v[200:203], v188 offset:4096
	ds_read_b128 v[204:207], v188 offset:5120
	ds_read_b128 v[214:217], v188 offset:6144
	ds_read_b128 v[218:221], v188 offset:7168
	s_waitcnt vmcnt(8)
	s_waitcnt lgkmcnt(0)
	s_barrier
	s_setprio 1
	s_waitcnt lgkmcnt(0)
	v_mfma_f32_16x16x32_bf16 v[128:131], v[132:135], v[170:173], v[128:131]
	v_mfma_f32_16x16x32_bf16 v[124:127], v[140:143], v[170:173], v[124:127]
	v_mfma_f32_16x16x32_bf16 v[116:119], v[132:135], v[192:195], v[116:119]
	v_mfma_f32_16x16x32_bf16 v[112:115], v[140:143], v[192:195], v[112:115]
	v_mfma_f32_16x16x32_bf16 v[96:99], v[132:135], v[200:203], v[96:99]
	v_mfma_f32_16x16x32_bf16 v[92:95], v[140:143], v[200:203], v[92:95]
	v_mfma_f32_16x16x32_bf16 v[80:83], v[132:135], v[214:217], v[80:83]
	v_mfma_f32_16x16x32_bf16 v[84:87], v[140:143], v[214:217], v[84:87]
	v_mfma_f32_16x16x32_bf16 v[128:131], v[136:139], v[174:177], v[128:131]
	v_mfma_f32_16x16x32_bf16 v[124:127], v[144:147], v[174:177], v[124:127]
	v_mfma_f32_16x16x32_bf16 v[116:119], v[136:139], v[196:199], v[116:119]
	v_mfma_f32_16x16x32_bf16 v[112:115], v[144:147], v[196:199], v[112:115]
	v_mfma_f32_16x16x32_bf16 v[96:99], v[136:139], v[204:207], v[96:99]
	v_mfma_f32_16x16x32_bf16 v[92:95], v[144:147], v[204:207], v[92:95]
	v_mfma_f32_16x16x32_bf16 v[80:83], v[136:139], v[218:221], v[80:83]
	v_mfma_f32_16x16x32_bf16 v[84:87], v[144:147], v[218:221], v[84:87]
	s_setprio 0
	s_setprio 1
	v_mfma_f32_16x16x32_bf16 v[120:123], v[148:151], v[170:173], v[120:123]
	v_mfma_f32_16x16x32_bf16 v[108:111], v[156:159], v[170:173], v[108:111]
	v_mfma_f32_16x16x32_bf16 v[104:107], v[148:151], v[192:195], v[104:107]
	v_mfma_f32_16x16x32_bf16 v[100:103], v[156:159], v[192:195], v[100:103]
	v_mfma_f32_16x16x32_bf16 v[88:91], v[148:151], v[200:203], v[88:91]
	v_mfma_f32_16x16x32_bf16 v[72:75], v[156:159], v[200:203], v[72:75]
	v_mfma_f32_16x16x32_bf16 v[68:71], v[148:151], v[214:217], v[68:71]
	v_mfma_f32_16x16x32_bf16 v[64:67], v[156:159], v[214:217], v[64:67]
	v_mfma_f32_16x16x32_bf16 v[120:123], v[152:155], v[174:177], v[120:123]
	v_mfma_f32_16x16x32_bf16 v[108:111], v[166:169], v[174:177], v[108:111]
	v_mfma_f32_16x16x32_bf16 v[104:107], v[152:155], v[196:199], v[104:107]
	v_mfma_f32_16x16x32_bf16 v[100:103], v[166:169], v[196:199], v[100:103]
	v_mfma_f32_16x16x32_bf16 v[88:91], v[152:155], v[204:207], v[88:91]
	v_mfma_f32_16x16x32_bf16 v[72:75], v[166:169], v[204:207], v[72:75]
	v_mfma_f32_16x16x32_bf16 v[68:71], v[152:155], v[218:221], v[68:71]
	v_mfma_f32_16x16x32_bf16 v[64:67], v[166:169], v[218:221], v[64:67]
	s_setprio 0
	s_barrier
	s_add_i32 s27, s27, s78
	v_lshl_add_u64 v[178:179], s[22:23], 0, v[2:3]
	s_mov_b32 m0, s27
	s_nop 0
	global_load_lds_dwordx4 v[178:179], off
	s_add_i32 m0, s27, 0x2000
	s_add_u32 s50, s22, 0x4000
	v_lshl_add_u64 v[178:179], s[22:23], 0, v[160:161]
	s_addc_u32 s51, s23, 0
	s_add_i32 s27, s45, s78
	global_load_lds_dwordx4 v[178:179], off
	v_lshl_add_u64 v[178:179], s[50:51], 0, v[2:3]
	s_mov_b32 m0, s27
	s_nop 0
	global_load_lds_dwordx4 v[178:179], off
	v_lshl_add_u64 v[178:179], s[50:51], 0, v[160:161]
	s_add_i32 m0, s27, 0x2000
	s_nop 0
	global_load_lds_dwordx4 v[178:179], off
	v_lshl_add_u64 v[178:179], s[24:25], 0, v[2:3]
	s_mov_b32 m0, s79
	s_nop 0
	global_load_lds_dwordx4 v[178:179], off
	v_lshl_add_u64 v[178:179], s[24:25], 0, v[160:161]
	s_mov_b32 m0, s40
	s_nop 0
	global_load_lds_dwordx4 v[178:179], off
	ds_read_b128 v[170:173], v188 offset:16384
	ds_read_b128 v[174:177], v188 offset:17408
	ds_read_b128 v[192:195], v188 offset:18432
	ds_read_b128 v[196:199], v188 offset:19456
	ds_read_b128 v[200:203], v188 offset:20480
	ds_read_b128 v[204:207], v188 offset:21504
	ds_read_b128 v[214:217], v188 offset:22528
	ds_read_b128 v[218:221], v188 offset:23552
	s_waitcnt vmcnt(8)
	s_waitcnt lgkmcnt(0)
	s_barrier
	s_setprio 1
	s_waitcnt lgkmcnt(0)
	v_mfma_f32_16x16x32_bf16 v[60:63], v[132:135], v[170:173], v[60:63]
	v_mfma_f32_16x16x32_bf16 v[56:59], v[140:143], v[170:173], v[56:59]
	v_mfma_f32_16x16x32_bf16 v[44:47], v[132:135], v[192:195], v[44:47]
	v_mfma_f32_16x16x32_bf16 v[48:51], v[140:143], v[192:195], v[48:51]
	v_mfma_f32_16x16x32_bf16 v[28:31], v[132:135], v[200:203], v[28:31]
	v_mfma_f32_16x16x32_bf16 v[24:27], v[140:143], v[200:203], v[24:27]
	v_mfma_f32_16x16x32_bf16 v[76:79], v[132:135], v[214:217], v[76:79]
	v_mfma_f32_16x16x32_bf16 v[16:19], v[140:143], v[214:217], v[16:19]
	v_mfma_f32_16x16x32_bf16 v[60:63], v[136:139], v[174:177], v[60:63]
	v_mfma_f32_16x16x32_bf16 v[56:59], v[144:147], v[174:177], v[56:59]
	v_mfma_f32_16x16x32_bf16 v[44:47], v[136:139], v[196:199], v[44:47]
	v_mfma_f32_16x16x32_bf16 v[48:51], v[144:147], v[196:199], v[48:51]
	v_mfma_f32_16x16x32_bf16 v[28:31], v[136:139], v[204:207], v[28:31]
	v_mfma_f32_16x16x32_bf16 v[24:27], v[144:147], v[204:207], v[24:27]
	v_mfma_f32_16x16x32_bf16 v[76:79], v[136:139], v[218:221], v[76:79]
	v_mfma_f32_16x16x32_bf16 v[16:19], v[144:147], v[218:221], v[16:19]
	s_setprio 0
	s_setprio 1
	v_mfma_f32_16x16x32_bf16 v[52:55], v[148:151], v[170:173], v[52:55]
	v_mfma_f32_16x16x32_bf16 v[40:43], v[156:159], v[170:173], v[40:43]
	v_mfma_f32_16x16x32_bf16 v[36:39], v[148:151], v[192:195], v[36:39]
	v_mfma_f32_16x16x32_bf16 v[32:35], v[156:159], v[192:195], v[32:35]
	v_mfma_f32_16x16x32_bf16 v[20:23], v[148:151], v[200:203], v[20:23]
	v_mfma_f32_16x16x32_bf16 v[12:15], v[156:159], v[200:203], v[12:15]
	v_mfma_f32_16x16x32_bf16 v[4:7], v[148:151], v[214:217], v[4:7]
	v_mfma_f32_16x16x32_bf16 v[8:11], v[156:159], v[214:217], v[8:11]
	v_mfma_f32_16x16x32_bf16 v[52:55], v[152:155], v[174:177], v[52:55]
	v_mfma_f32_16x16x32_bf16 v[40:43], v[166:169], v[174:177], v[40:43]
	v_mfma_f32_16x16x32_bf16 v[36:39], v[152:155], v[196:199], v[36:39]
	v_mfma_f32_16x16x32_bf16 v[32:35], v[166:169], v[196:199], v[32:35]
	v_mfma_f32_16x16x32_bf16 v[20:23], v[152:155], v[204:207], v[20:23]
	v_mfma_f32_16x16x32_bf16 v[12:15], v[166:169], v[204:207], v[12:15]
	v_mfma_f32_16x16x32_bf16 v[4:7], v[152:155], v[218:221], v[4:7]
	v_mfma_f32_16x16x32_bf16 v[8:11], v[166:169], v[218:221], v[8:11]
	s_setprio 0
	s_barrier
	s_add_i32 s27, 0, 0x18000
	s_add_i32 s45, 0, 0x1c000
	s_add_u32 s24, s24, 0x4000
	s_addc_u32 s25, s25, 0
	s_mov_b32 m0, s41
	v_lshl_add_u64 v[178:179], s[24:25], 0, v[2:3]
	global_load_lds_dwordx4 v[178:179], off
	v_lshl_add_u64 v[178:179], s[24:25], 0, v[160:161]
	s_mov_b32 m0, s46
	s_nop 0
	global_load_lds_dwordx4 v[178:179], off
	v_add_u32_e32 v144, s27, v180
	v_add_u32_e32 v166, s45, v180
	ds_read_b128 v[132:135], v144
	ds_read_b128 v[136:139], v144 offset:1024
	ds_read_b128 v[140:143], v144 offset:2048
	ds_read_b128 v[144:147], v144 offset:3072
	ds_read_b128 v[148:151], v166
	ds_read_b128 v[152:155], v166 offset:1024
	ds_read_b128 v[156:159], v166 offset:2048
	ds_read_b128 v[166:169], v166 offset:3072
	ds_read_b128 v[170:173], v188 offset:32768
	ds_read_b128 v[174:177], v188 offset:33792
	ds_read_b128 v[192:195], v188 offset:34816
	ds_read_b128 v[196:199], v188 offset:35840
	ds_read_b128 v[200:203], v188 offset:36864
	ds_read_b128 v[204:207], v188 offset:37888
	ds_read_b128 v[214:217], v188 offset:38912
	ds_read_b128 v[218:221], v188 offset:39936
	s_waitcnt vmcnt(8)
	s_waitcnt lgkmcnt(0)
	s_barrier
	s_setprio 1
	s_waitcnt lgkmcnt(0)
	v_mfma_f32_16x16x32_bf16 v[128:131], v[132:135], v[170:173], v[128:131]
	v_mfma_f32_16x16x32_bf16 v[124:127], v[140:143], v[170:173], v[124:127]
	v_mfma_f32_16x16x32_bf16 v[116:119], v[132:135], v[192:195], v[116:119]
	v_mfma_f32_16x16x32_bf16 v[112:115], v[140:143], v[192:195], v[112:115]
	v_mfma_f32_16x16x32_bf16 v[96:99], v[132:135], v[200:203], v[96:99]
	v_mfma_f32_16x16x32_bf16 v[92:95], v[140:143], v[200:203], v[92:95]
	v_mfma_f32_16x16x32_bf16 v[80:83], v[132:135], v[214:217], v[80:83]
	v_mfma_f32_16x16x32_bf16 v[84:87], v[140:143], v[214:217], v[84:87]
	v_mfma_f32_16x16x32_bf16 v[128:131], v[136:139], v[174:177], v[128:131]
	v_mfma_f32_16x16x32_bf16 v[124:127], v[144:147], v[174:177], v[124:127]
	v_mfma_f32_16x16x32_bf16 v[116:119], v[136:139], v[196:199], v[116:119]
	v_mfma_f32_16x16x32_bf16 v[112:115], v[144:147], v[196:199], v[112:115]
	v_mfma_f32_16x16x32_bf16 v[96:99], v[136:139], v[204:207], v[96:99]
	v_mfma_f32_16x16x32_bf16 v[92:95], v[144:147], v[204:207], v[92:95]
	v_mfma_f32_16x16x32_bf16 v[80:83], v[136:139], v[218:221], v[80:83]
	v_mfma_f32_16x16x32_bf16 v[84:87], v[144:147], v[218:221], v[84:87]
	s_setprio 0
	s_setprio 1
	v_mfma_f32_16x16x32_bf16 v[120:123], v[148:151], v[170:173], v[120:123]
	v_mfma_f32_16x16x32_bf16 v[108:111], v[156:159], v[170:173], v[108:111]
	v_mfma_f32_16x16x32_bf16 v[104:107], v[148:151], v[192:195], v[104:107]
	v_mfma_f32_16x16x32_bf16 v[100:103], v[156:159], v[192:195], v[100:103]
	v_mfma_f32_16x16x32_bf16 v[88:91], v[148:151], v[200:203], v[88:91]
	v_mfma_f32_16x16x32_bf16 v[72:75], v[156:159], v[200:203], v[72:75]
	v_mfma_f32_16x16x32_bf16 v[68:71], v[148:151], v[214:217], v[68:71]
	v_mfma_f32_16x16x32_bf16 v[64:67], v[156:159], v[214:217], v[64:67]
	v_mfma_f32_16x16x32_bf16 v[120:123], v[152:155], v[174:177], v[120:123]
	v_mfma_f32_16x16x32_bf16 v[108:111], v[166:169], v[174:177], v[108:111]
	v_mfma_f32_16x16x32_bf16 v[104:107], v[152:155], v[196:199], v[104:107]
	v_mfma_f32_16x16x32_bf16 v[100:103], v[166:169], v[196:199], v[100:103]
	v_mfma_f32_16x16x32_bf16 v[88:91], v[152:155], v[204:207], v[88:91]
	v_mfma_f32_16x16x32_bf16 v[72:75], v[166:169], v[204:207], v[72:75]
	v_mfma_f32_16x16x32_bf16 v[68:71], v[152:155], v[218:221], v[68:71]
	v_mfma_f32_16x16x32_bf16 v[64:67], v[166:169], v[218:221], v[64:67]
	s_setprio 0
	s_barrier
	s_add_u32 s24, s22, 0x8000
	s_addc_u32 s25, s23, 0
	s_add_i32 s27, s27, s78
	v_lshl_add_u64 v[178:179], s[24:25], 0, v[2:3]
	s_mov_b32 m0, s27
	s_nop 0
	global_load_lds_dwordx4 v[178:179], off
	s_add_i32 m0, s27, 0x2000
	s_add_u32 s22, s22, 0xc000
	v_lshl_add_u64 v[178:179], s[24:25], 0, v[160:161]
	s_addc_u32 s23, s23, 0
	s_add_i32 s24, s45, s78
	global_load_lds_dwordx4 v[178:179], off
	v_lshl_add_u64 v[178:179], s[22:23], 0, v[2:3]
	s_mov_b32 m0, s24
	s_nop 0
	global_load_lds_dwordx4 v[178:179], off
	v_lshl_add_u64 v[178:179], s[22:23], 0, v[160:161]
	s_add_i32 m0, s24, 0x2000
	s_nop 0
	global_load_lds_dwordx4 v[178:179], off
	v_lshl_add_u64 v[178:179], s[20:21], 0, v[2:3]
	s_mov_b32 m0, s52
	s_nop 0
	global_load_lds_dwordx4 v[178:179], off
	v_lshl_add_u64 v[178:179], s[20:21], 0, v[160:161]
	s_mov_b32 m0, s53
	s_nop 0
	global_load_lds_dwordx4 v[178:179], off
	ds_read_b128 v[170:173], v188 offset:49152
	ds_read_b128 v[174:177], v188 offset:50176
	ds_read_b128 v[192:195], v188 offset:51200
	ds_read_b128 v[196:199], v188 offset:52224
	ds_read_b128 v[200:203], v188 offset:53248
	ds_read_b128 v[204:207], v188 offset:54272
	ds_read_b128 v[214:217], v188 offset:55296
	ds_read_b128 v[218:221], v188 offset:56320
	s_waitcnt vmcnt(8)
	s_waitcnt lgkmcnt(0)
	s_barrier
	s_setprio 1
	s_waitcnt lgkmcnt(0)
	v_mfma_f32_16x16x32_bf16 v[60:63], v[132:135], v[170:173], v[60:63]
	v_mfma_f32_16x16x32_bf16 v[56:59], v[140:143], v[170:173], v[56:59]
	v_mfma_f32_16x16x32_bf16 v[44:47], v[132:135], v[192:195], v[44:47]
	v_mfma_f32_16x16x32_bf16 v[48:51], v[140:143], v[192:195], v[48:51]
	v_mfma_f32_16x16x32_bf16 v[28:31], v[132:135], v[200:203], v[28:31]
	v_mfma_f32_16x16x32_bf16 v[24:27], v[140:143], v[200:203], v[24:27]
	v_mfma_f32_16x16x32_bf16 v[76:79], v[132:135], v[214:217], v[76:79]
	v_mfma_f32_16x16x32_bf16 v[16:19], v[140:143], v[214:217], v[16:19]
	v_mfma_f32_16x16x32_bf16 v[60:63], v[136:139], v[174:177], v[60:63]
	v_mfma_f32_16x16x32_bf16 v[56:59], v[144:147], v[174:177], v[56:59]
	v_mfma_f32_16x16x32_bf16 v[44:47], v[136:139], v[196:199], v[44:47]
	v_mfma_f32_16x16x32_bf16 v[48:51], v[144:147], v[196:199], v[48:51]
	v_mfma_f32_16x16x32_bf16 v[28:31], v[136:139], v[204:207], v[28:31]
	v_mfma_f32_16x16x32_bf16 v[24:27], v[144:147], v[204:207], v[24:27]
	v_mfma_f32_16x16x32_bf16 v[76:79], v[136:139], v[218:221], v[76:79]
	v_mfma_f32_16x16x32_bf16 v[16:19], v[144:147], v[218:221], v[16:19]
	s_setprio 0
	s_setprio 1
	v_mfma_f32_16x16x32_bf16 v[52:55], v[148:151], v[170:173], v[52:55]
	v_mfma_f32_16x16x32_bf16 v[40:43], v[156:159], v[170:173], v[40:43]
	v_mfma_f32_16x16x32_bf16 v[36:39], v[148:151], v[192:195], v[36:39]
	v_mfma_f32_16x16x32_bf16 v[32:35], v[156:159], v[192:195], v[32:35]
	v_mfma_f32_16x16x32_bf16 v[20:23], v[148:151], v[200:203], v[20:23]
	v_mfma_f32_16x16x32_bf16 v[12:15], v[156:159], v[200:203], v[12:15]
	v_mfma_f32_16x16x32_bf16 v[4:7], v[148:151], v[214:217], v[4:7]
	v_mfma_f32_16x16x32_bf16 v[8:11], v[156:159], v[214:217], v[8:11]
	v_mfma_f32_16x16x32_bf16 v[52:55], v[152:155], v[174:177], v[52:55]
	v_mfma_f32_16x16x32_bf16 v[40:43], v[166:169], v[174:177], v[40:43]
	v_mfma_f32_16x16x32_bf16 v[36:39], v[152:155], v[196:199], v[36:39]
	v_mfma_f32_16x16x32_bf16 v[32:35], v[166:169], v[196:199], v[32:35]
	v_mfma_f32_16x16x32_bf16 v[20:23], v[152:155], v[204:207], v[20:23]
	v_mfma_f32_16x16x32_bf16 v[12:15], v[166:169], v[204:207], v[12:15]
	v_mfma_f32_16x16x32_bf16 v[4:7], v[152:155], v[218:221], v[4:7]
	v_mfma_f32_16x16x32_bf16 v[8:11], v[166:169], v[218:221], v[8:11]
	s_setprio 0
	s_barrier
	s_add_i32 s26, s26, 2
	s_add_u32 s18, s18, 0x10000
	s_addc_u32 s19, s19, 0
	s_add_u32 s6, s6, 0x10000
	s_addc_u32 s7, s7, 0
	s_cmpk_gt_u32 s26, 0x55
	s_cbranch_scc0 .LBB0_810
	v_readlane_b32 s6, v254, 33
	v_readlane_b32 s7, v254, 34
	s_and_b64 vcc, exec, s[6:7]
	s_cbranch_vccz .LBB0_813
	s_barrier
